# P4 epilogue path A uses packed f32 (pk_mul/pk_add) for scale/add/mul stages; ret_sample gate loads hoisted; remaining IEEE div chains -> rcp+NR
# speedup vs baseline: 1.0324x; 1.0057x over previous
; DEV float sigmoidf_(float x) { return 1.0f / (1.0f + __expf(-x)); }
; DEV void sg_ple(const Params& p, unsigned char* smem) {
;     ...
;     sg_core<4>(Pb + (size_t)TP * DPLE, DPLE, Wpp, DPLE, DPLE, row0, col0, pr, smem);
;     f32x4 acc[2]; acc[0] = (f32x4){0.f, 0.f, 0.f, 0.f}; acc[1] = (f32x4){0.f, 0.f, 0.f, 0.f};
;     sg_core<8>(H + (size_t)TP * D, D, Wpg, D, D, row0, col0, acc, smem);
;     SG_EPI({
;       float* xp = X + row * D + col;
;       f32x4 x = *(const f32x4*)xp;
;       x[0] += sigmoidf_(acc[ni][0]) * pr[ni][0]; x[1] += sigmoidf_(acc[ni][1]) * pr[ni][1]; x[2] += sigmoidf_(acc[ni][2]) * pr[ni][2]; x[3] += sigmoidf_(acc[ni][3]) * pr[ni][3];
;       *(f32x4*)xp = x;
;     })
.LBB0_97:
	v_mfma_f32_16x16x32_bf16 v[8:11], v[8:11], v[0:3], 0
	s_ashr_i32 s12, s17, 31
	s_add_u32 s13, s17, 0x4000
	s_addc_u32 s12, s12, 0
	v_mfma_f32_16x16x32_bf16 v[0:3], v[12:15], v[0:3], 0
	v_mov_b32_e32 v12, v171
	v_mov_b32_e32 v13, v171
	v_mfma_f32_16x16x32_bf16 v[8:11], v[16:19], v[4:7], v[8:11]
	v_mul_f32_e32 v14, 0xbfb8aa3b, v164
	v_mul_f32_e32 v15, 0xbfb8aa3b, v165
	v_mfma_f32_16x16x32_bf16 v[0:3], v[20:23], v[4:7], v[0:3]
	v_exp_f32_e32 v14, v14
	v_exp_f32_e32 v15, v15
	v_mul_f32_e32 v16, 0xbfb8aa3b, v166
	v_mfma_f32_16x16x32_bf16 v[4:7], v[32:35], v[24:27], v[8:11]
	v_mul_f32_e32 v17, 0xbfb8aa3b, v167
	v_pk_add_f32 v[14:15], v[14:15], 1.0 op_sel_hi:[1,0]
	v_exp_f32_e32 v16, v16
	v_ashrrev_i32_e32 v8, 3, v13
	v_and_b32_e32 v8, -16, v8
	v_ashrrev_i32_e32 v9, 31, v8
	v_and_or_b32 v10, v12, 15, s13
	v_mov_b32_e32 v11, s12
	v_lshl_add_u64 v[8:9], v[10:11], 0, v[8:9]
	v_lshrrev_b32_e32 v10, 1, v13
	v_lshrrev_b32_e32 v11, 2, v12
	v_and_b32_e32 v10, 32, v10
	v_and_b32_e32 v11, 12, v11
	v_or3_b32 v10, v11, v10, s16
	v_lshlrev_b64 v[8:9], 12, v[8:9]
	v_lshl_add_u64 v[8:9], s[22:23], 0, v[8:9]
	v_lshlrev_b32_e32 v168, 2, v10
	v_lshl_add_u64 v[8:9], v[8:9], 0, v[168:169]
	global_load_dwordx4 v[10:13], v[8:9], off
	v_rcp_f32_e32 v19, v15
	v_exp_f32_e32 v17, v17
	v_mfma_f32_16x16x32_bf16 v[4:7], v[40:43], v[28:31], v[4:7]
	v_fma_f32 v20, -v15, v19, 1.0
	v_fmac_f32_e32 v19, v20, v19
	v_mov_b32_e32 v15, v19
	v_rcp_f32_e32 v19, v14
	v_pk_add_f32 v[16:17], v[16:17], 1.0 op_sel_hi:[1,0]
	v_mfma_f32_16x16x32_bf16 v[4:7], v[56:59], v[48:51], v[4:7]
	v_fma_f32 v20, -v14, v19, 1.0
	v_fmac_f32_e32 v19, v20, v19
	v_mov_b32_e32 v14, v19
	v_rcp_f32_e32 v19, v17
	v_mfma_f32_16x16x32_bf16 v[4:7], v[64:67], v[52:55], v[4:7]
	v_fma_f32 v20, -v17, v19, 1.0
	v_fmac_f32_e32 v19, v20, v19
	v_mov_b32_e32 v17, v19
	v_rcp_f32_e32 v19, v16
	v_mfma_f32_16x16x32_bf16 v[4:7], v[72:75], v[76:79], v[4:7]
	v_fma_f32 v20, -v16, v19, 1.0
	v_fmac_f32_e32 v19, v20, v19
	v_mfma_f32_16x16x32_bf16 v[4:7], v[88:91], v[80:83], v[4:7]
	v_mov_b32_e32 v16, v19
	v_mfma_f32_16x16x32_bf16 v[0:3], v[36:39], v[24:27], v[0:3]
	s_waitcnt vmcnt(0)
	s_nop 1
	s_nop 2
	v_pk_fma_f32 v[6:7], v[16:17], v[6:7], v[12:13]
	s_nop 1
	v_pk_fma_f32 v[4:5], v[14:15], v[4:5], v[10:11]
	s_nop 0
	global_store_dwordx4 v[8:9], v[4:7], off
	global_load_dwordx4 v[4:7], v[8:9], off offset:64
	v_mul_f32_e32 v10, 0xbfb8aa3b, v160
	v_mul_f32_e32 v11, 0xbfb8aa3b, v161
	v_exp_f32_e32 v10, v10
	v_exp_f32_e32 v11, v11
	v_mul_f32_e32 v12, 0xbfb8aa3b, v162
	v_mul_f32_e32 v13, 0xbfb8aa3b, v163
	v_exp_f32_e32 v12, v12
	v_pk_add_f32 v[10:11], v[10:11], 1.0 op_sel_hi:[1,0]
	v_exp_f32_e32 v13, v13
	v_rcp_f32_e32 v15, v11
	v_pk_add_f32 v[12:13], v[12:13], 1.0 op_sel_hi:[1,0]
	v_mfma_f32_16x16x32_bf16 v[0:3], v[44:47], v[28:31], v[0:3]
	v_fma_f32 v16, -v11, v15, 1.0
	v_fmac_f32_e32 v15, v16, v15
	v_mov_b32_e32 v11, v15
	v_rcp_f32_e32 v15, v10
	v_mfma_f32_16x16x32_bf16 v[0:3], v[60:63], v[48:51], v[0:3]
	v_fma_f32 v16, -v10, v15, 1.0
	v_fmac_f32_e32 v15, v16, v15
	v_mov_b32_e32 v10, v15
	v_rcp_f32_e32 v15, v13
	v_mfma_f32_16x16x32_bf16 v[0:3], v[68:71], v[52:55], v[0:3]
	v_fma_f32 v16, -v13, v15, 1.0
	v_fmac_f32_e32 v15, v16, v15
	v_mov_b32_e32 v13, v15
	v_rcp_f32_e32 v15, v12
	v_mfma_f32_16x16x32_bf16 v[0:3], v[84:87], v[76:79], v[0:3]
	v_readlane_b32 s12, v248, 37
	v_readlane_b32 s14, v248, 39
	v_fma_f32 v16, -v12, v15, 1.0
	v_fmac_f32_e32 v15, v16, v15
	v_mfma_f32_16x16x32_bf16 v[0:3], v[92:95], v[80:83], v[0:3]
	v_mov_b32_e32 v12, v15
	s_add_i32 s6, s6, s14
	s_cmpk_lt_i32 s6, 0x100
	v_readlane_b32 s13, v248, 38
	v_readlane_b32 s15, v248, 40
	s_waitcnt vmcnt(0)
	s_nop 1
	v_pk_fma_f32 v[2:3], v[12:13], v[2:3], v[6:7]
	s_nop 0
	v_pk_fma_f32 v[0:1], v[10:11], v[0:1], v[4:5]
	global_store_dwordx4 v[8:9], v[0:3], off offset:64
	s_cbranch_scc0 .LBB0_116

; DEV float bflo(unsigned w) { return __uint_as_float(w << 16); }
; DEV float bfhi(unsigned w) { return __uint_as_float(w & 0xffff0000u); }
; #define RS_(xa, xb) ((1.0f + one * __expf(-(xb))) * __builtin_amdgcn_rcpf(1.0f + __expf(-(xa))))
;   DEV bool rescale(f32x4 (&acc)[2][2][4][2], const Unit& u, int wr, int wc, int fr, int fq) const {
;     const int row0 = u.pm * BM + wr * 64 + fr, col0 = u.pn * BM + wc * 32 + 8 * fq;
;     const bool lastseg = u.seg == 2;
;     const int sb = lastseg ? 2 : u.seg + 1;
;     const float one = lastseg ? 0.f : 1.f;
; #pragma unroll
;     for (int ai = 0; ai < 2; ++ai)
; #pragma unroll
;       for (int m = 0; m < 4; ++m) {
;         const size_t r = (size_t)(row0 + ai * HALF + m * 16);
; #pragma unroll
;         for (int bj = 0; bj < 2; ++bj) {
;           const int c = col0 + bj * HALF;
;           const u32x4 ga = *(const u32x4*)(Z + r * NIN + GT + u.seg * D + c);
;           const u32x4 gb = *(const u32x4*)(Z + r * NIN + GT + sb * D + c);
;     ...
;           acc[ai][bj][m][0][0] *= RS_(bflo(ga.x), bflo(gb.x)); acc[ai][bj][m][0][1] *= RS_(bfhi(ga.x), bfhi(gb.x));
;           acc[ai][bj][m][0][2] *= RS_(bflo(ga.y), bflo(gb.y)); acc[ai][bj][m][0][3] *= RS_(bfhi(ga.y), bfhi(gb.y));
;           acc[ai][bj][m][1][0] *= RS_(bflo(ga.z), bflo(gb.z)); acc[ai][bj][m][1][1] *= RS_(bfhi(ga.z), bfhi(gb.z));
;           acc[ai][bj][m][1][2] *= RS_(bflo(ga.w), bflo(gb.w)); acc[ai][bj][m][1][3] *= RS_(bfhi(ga.w), bfhi(gb.w));
;     ...
;           asm volatile("" ::: "memory");
;         }
.LBB0_320:
	v_lshl_add_u32 v144, s49, 8, v147
	v_lshl_or_b32 v145, s50, 8, v163
	v_mov_b64_e32 v[218:219], s[30:31]
	s_lshl_b32 s18, s48, 11
	s_add_i32 s18, s18, 0x1e00
	s_mov_b32 s19, 0
	v_lshlrev_b32_e32 v145, 1, v145
	v_mad_i64_i32 v[142:143], s[26:27], v144, s95, v[218:219]
	s_mov_b32 s20, 0x36000
	s_mov_b32 s21, 0
	v_lshl_add_u64 v[142:143], v[142:143], 0, s[18:19]
	s_mov_b32 s26, 0x10e000
	s_mov_b32 s27, 0
	v_add_co_u32_e32 v218, vcc, v142, v145
	s_nop 1
	v_addc_co_u32_e32 v219, vcc, 0, v143, vcc
	s_cmp_eq_u32 s48, 2
	s_cselect_b64 s[0:1], -1, 0
	s_cbranch_scc1 .Lp4epi_last
	s_mov_b32 s18, 0xbfb8aa3b
	s_mov_b32 s19, 0xbfb8aa3b
	global_load_dwordx4 v[180:183], v[218:219], off
	global_load_dwordx4 v[188:191], v[218:219], off offset:2048
	global_load_dwordx4 v[184:187], v[218:219], off offset:256
	global_load_dwordx4 v[192:195], v[218:219], off offset:2304
	v_lshl_add_u64 v[218:219], v[218:219], 0, s[20:21]
	global_load_dwordx4 v[196:199], v[218:219], off
	global_load_dwordx4 v[224:227], v[218:219], off offset:2048
	global_load_dwordx4 v[220:223], v[218:219], off offset:256
	global_load_dwordx4 v[228:231], v[218:219], off offset:2304
	v_lshl_add_u64 v[218:219], v[218:219], 0, s[20:21]
	global_load_dwordx4 v[232:235], v[218:219], off
	global_load_dwordx4 v[240:243], v[218:219], off offset:2048
	global_load_dwordx4 v[236:239], v[218:219], off offset:256
	global_load_dwordx4 v[148:151], v[218:219], off offset:2304
	v_lshl_add_u64 v[218:219], v[218:219], 0, s[20:21]
	s_waitcnt vmcnt(8)
	v_lshlrev_b32_e32 v128, 16, v180
	v_and_b32_e32 v129, 0xffff0000, v180
	v_lshlrev_b32_e32 v156, 16, v188
	v_and_b32_e32 v157, 0xffff0000, v188
	v_lshlrev_b32_e32 v130, 16, v181
	v_and_b32_e32 v131, 0xffff0000, v181
	v_lshlrev_b32_e32 v158, 16, v189
	v_and_b32_e32 v159, 0xffff0000, v189
	v_lshlrev_b32_e32 v152, 16, v182
	v_and_b32_e32 v153, 0xffff0000, v182
	v_lshlrev_b32_e32 v160, 16, v190
	v_and_b32_e32 v161, 0xffff0000, v190
	v_lshlrev_b32_e32 v154, 16, v183
	v_and_b32_e32 v155, 0xffff0000, v183
	v_lshlrev_b32_e32 v166, 16, v191
	v_and_b32_e32 v167, 0xffff0000, v191
	v_pk_mul_f32 v[128:129], v[128:129], s[18:19]
	v_pk_mul_f32 v[156:157], v[156:157], s[18:19]
	v_pk_mul_f32 v[130:131], v[130:131], s[18:19]
	v_pk_mul_f32 v[158:159], v[158:159], s[18:19]
	v_pk_mul_f32 v[152:153], v[152:153], s[18:19]
	v_pk_mul_f32 v[160:161], v[160:161], s[18:19]
	v_pk_mul_f32 v[154:155], v[154:155], s[18:19]
	v_pk_mul_f32 v[166:167], v[166:167], s[18:19]
	v_exp_f32_e32 v128, v128
	v_exp_f32_e32 v129, v129
	v_exp_f32_e32 v156, v156
	v_exp_f32_e32 v157, v157
	v_exp_f32_e32 v130, v130
	v_exp_f32_e32 v131, v131
	v_exp_f32_e32 v158, v158
	v_exp_f32_e32 v159, v159
	v_exp_f32_e32 v152, v152
	v_exp_f32_e32 v153, v153
	v_exp_f32_e32 v160, v160
	v_exp_f32_e32 v161, v161
	v_exp_f32_e32 v154, v154
	v_exp_f32_e32 v155, v155
	v_exp_f32_e32 v166, v166
	v_exp_f32_e32 v167, v167
	v_pk_add_f32 v[128:129], v[128:129], 1.0 op_sel_hi:[1,0]
	v_pk_add_f32 v[156:157], v[156:157], 1.0 op_sel_hi:[1,0]
	v_pk_add_f32 v[130:131], v[130:131], 1.0 op_sel_hi:[1,0]
	v_pk_add_f32 v[158:159], v[158:159], 1.0 op_sel_hi:[1,0]
	v_pk_add_f32 v[152:153], v[152:153], 1.0 op_sel_hi:[1,0]
	v_pk_add_f32 v[160:161], v[160:161], 1.0 op_sel_hi:[1,0]
	v_pk_add_f32 v[154:155], v[154:155], 1.0 op_sel_hi:[1,0]
	v_pk_add_f32 v[166:167], v[166:167], 1.0 op_sel_hi:[1,0]
	v_rcp_f32_e32 v128, v128
	v_rcp_f32_e32 v129, v129
	v_rcp_f32_e32 v130, v130
	v_rcp_f32_e32 v131, v131
	v_rcp_f32_e32 v152, v152
	v_rcp_f32_e32 v153, v153
	v_rcp_f32_e32 v154, v154
	v_rcp_f32_e32 v155, v155
	v_pk_mul_f32 v[128:129], v[128:129], v[156:157]
	v_pk_mul_f32 v[130:131], v[130:131], v[158:159]
	v_pk_mul_f32 v[152:153], v[152:153], v[160:161]
	v_pk_mul_f32 v[154:155], v[154:155], v[166:167]
	v_pk_mul_f32 v[124:125], v[124:125], v[128:129]
	v_pk_mul_f32 v[126:127], v[126:127], v[130:131]
	v_pk_mul_f32 v[120:121], v[120:121], v[152:153]
	v_pk_mul_f32 v[122:123], v[122:123], v[154:155]
	v_lshlrev_b32_e32 v128, 16, v184
	v_and_b32_e32 v129, 0xffff0000, v184
	v_lshlrev_b32_e32 v156, 16, v192
	v_and_b32_e32 v157, 0xffff0000, v192
	v_lshlrev_b32_e32 v130, 16, v185
	v_and_b32_e32 v131, 0xffff0000, v185
	v_lshlrev_b32_e32 v158, 16, v193
	v_and_b32_e32 v159, 0xffff0000, v193
	v_lshlrev_b32_e32 v152, 16, v186
	v_and_b32_e32 v153, 0xffff0000, v186
	v_lshlrev_b32_e32 v160, 16, v194
	v_and_b32_e32 v161, 0xffff0000, v194
	v_lshlrev_b32_e32 v154, 16, v187
	v_and_b32_e32 v155, 0xffff0000, v187
	v_lshlrev_b32_e32 v166, 16, v195
	v_and_b32_e32 v167, 0xffff0000, v195
	v_pk_mul_f32 v[128:129], v[128:129], s[18:19]
	v_pk_mul_f32 v[156:157], v[156:157], s[18:19]
	v_pk_mul_f32 v[130:131], v[130:131], s[18:19]
	v_pk_mul_f32 v[158:159], v[158:159], s[18:19]
	v_pk_mul_f32 v[152:153], v[152:153], s[18:19]
	v_pk_mul_f32 v[160:161], v[160:161], s[18:19]
	v_pk_mul_f32 v[154:155], v[154:155], s[18:19]
	v_pk_mul_f32 v[166:167], v[166:167], s[18:19]
	v_exp_f32_e32 v128, v128
	v_exp_f32_e32 v129, v129
	v_exp_f32_e32 v156, v156
	v_exp_f32_e32 v157, v157
	v_exp_f32_e32 v130, v130
	v_exp_f32_e32 v131, v131
	v_exp_f32_e32 v158, v158
	v_exp_f32_e32 v159, v159
	v_exp_f32_e32 v152, v152
	v_exp_f32_e32 v153, v153
	v_exp_f32_e32 v160, v160
	v_exp_f32_e32 v161, v161
	v_exp_f32_e32 v154, v154
	v_exp_f32_e32 v155, v155
	v_exp_f32_e32 v166, v166
	v_exp_f32_e32 v167, v167
	v_pk_add_f32 v[128:129], v[128:129], 1.0 op_sel_hi:[1,0]
	v_pk_add_f32 v[156:157], v[156:157], 1.0 op_sel_hi:[1,0]
	v_pk_add_f32 v[130:131], v[130:131], 1.0 op_sel_hi:[1,0]
	v_pk_add_f32 v[158:159], v[158:159], 1.0 op_sel_hi:[1,0]
	v_pk_add_f32 v[152:153], v[152:153], 1.0 op_sel_hi:[1,0]
	v_pk_add_f32 v[160:161], v[160:161], 1.0 op_sel_hi:[1,0]
	v_pk_add_f32 v[154:155], v[154:155], 1.0 op_sel_hi:[1,0]
	v_pk_add_f32 v[166:167], v[166:167], 1.0 op_sel_hi:[1,0]
	v_rcp_f32_e32 v128, v128
	v_rcp_f32_e32 v129, v129
	v_rcp_f32_e32 v130, v130
	v_rcp_f32_e32 v131, v131
	v_rcp_f32_e32 v152, v152
	v_rcp_f32_e32 v153, v153
	v_rcp_f32_e32 v154, v154
	v_rcp_f32_e32 v155, v155
	v_pk_mul_f32 v[128:129], v[128:129], v[156:157]
	v_pk_mul_f32 v[130:131], v[130:131], v[158:159]
	v_pk_mul_f32 v[152:153], v[152:153], v[160:161]
	v_pk_mul_f32 v[154:155], v[154:155], v[166:167]
	v_pk_mul_f32 v[92:93], v[92:93], v[128:129]
	v_pk_mul_f32 v[94:95], v[94:95], v[130:131]
	v_pk_mul_f32 v[88:89], v[88:89], v[152:153]
	v_pk_mul_f32 v[90:91], v[90:91], v[154:155]
	global_load_dwordx4 v[180:183], v[218:219], off
	global_load_dwordx4 v[188:191], v[218:219], off offset:2048
	global_load_dwordx4 v[184:187], v[218:219], off offset:256
	global_load_dwordx4 v[192:195], v[218:219], off offset:2304
	v_lshl_add_u64 v[218:219], v[218:219], 0, s[26:27]
	s_waitcnt vmcnt(8)
; DEV float bflo(unsigned w) { return __uint_as_float(w << 16); }
; DEV float bfhi(unsigned w) { return __uint_as_float(w & 0xffff0000u); }
; #define RS_(xa, xb) ((1.0f + one * __expf(-(xb))) * __builtin_amdgcn_rcpf(1.0f + __expf(-(xa))))
;   DEV bool rescale(f32x4 (&acc)[2][2][4][2], const Unit& u, int wr, int wc, int fr, int fq) const {
;     ...
;     for (int ai = 0; ai < 2; ++ai)
; #pragma unroll
;       for (int m = 0; m < 4; ++m) {
;         const size_t r = (size_t)(row0 + ai * HALF + m * 16);
; #pragma unroll
;         for (int bj = 0; bj < 2; ++bj) {
;           const int c = col0 + bj * HALF;
;           const u32x4 ga = *(const u32x4*)(Z + r * NIN + GT + u.seg * D + c);
;           const u32x4 gb = *(const u32x4*)(Z + r * NIN + GT + sb * D + c);
;     ...
;           acc[ai][bj][m][0][0] *= RS_(bflo(ga.x), bflo(gb.x)); acc[ai][bj][m][0][1] *= RS_(bfhi(ga.x), bfhi(gb.x));
;           acc[ai][bj][m][0][2] *= RS_(bflo(ga.y), bflo(gb.y)); acc[ai][bj][m][0][3] *= RS_(bfhi(ga.y), bfhi(gb.y));
;           acc[ai][bj][m][1][0] *= RS_(bflo(ga.z), bflo(gb.z)); acc[ai][bj][m][1][1] *= RS_(bfhi(ga.z), bfhi(gb.z));
;           acc[ai][bj][m][1][2] *= RS_(bflo(ga.w), bflo(gb.w)); acc[ai][bj][m][1][3] *= RS_(bfhi(ga.w), bfhi(gb.w));
;     ...
;           asm volatile("" ::: "memory");
;         }
	v_lshlrev_b32_e32 v128, 16, v196
	v_and_b32_e32 v129, 0xffff0000, v196
	v_lshlrev_b32_e32 v156, 16, v224
	v_and_b32_e32 v157, 0xffff0000, v224
	v_lshlrev_b32_e32 v130, 16, v197
	v_and_b32_e32 v131, 0xffff0000, v197
	v_lshlrev_b32_e32 v158, 16, v225
	v_and_b32_e32 v159, 0xffff0000, v225
	v_lshlrev_b32_e32 v152, 16, v198
	v_and_b32_e32 v153, 0xffff0000, v198
	v_lshlrev_b32_e32 v160, 16, v226
	v_and_b32_e32 v161, 0xffff0000, v226
	v_lshlrev_b32_e32 v154, 16, v199
	v_and_b32_e32 v155, 0xffff0000, v199
	v_lshlrev_b32_e32 v166, 16, v227
	v_and_b32_e32 v167, 0xffff0000, v227
	v_pk_mul_f32 v[128:129], v[128:129], s[18:19]
	v_pk_mul_f32 v[156:157], v[156:157], s[18:19]
	v_pk_mul_f32 v[130:131], v[130:131], s[18:19]
	v_pk_mul_f32 v[158:159], v[158:159], s[18:19]
	v_pk_mul_f32 v[152:153], v[152:153], s[18:19]
	v_pk_mul_f32 v[160:161], v[160:161], s[18:19]
	v_pk_mul_f32 v[154:155], v[154:155], s[18:19]
	v_pk_mul_f32 v[166:167], v[166:167], s[18:19]
	v_exp_f32_e32 v128, v128
	v_exp_f32_e32 v129, v129
	v_exp_f32_e32 v156, v156
	v_exp_f32_e32 v157, v157
	v_exp_f32_e32 v130, v130
	v_exp_f32_e32 v131, v131
	v_exp_f32_e32 v158, v158
	v_exp_f32_e32 v159, v159
	v_exp_f32_e32 v152, v152
	v_exp_f32_e32 v153, v153
	v_exp_f32_e32 v160, v160
	v_exp_f32_e32 v161, v161
	v_exp_f32_e32 v154, v154
	v_exp_f32_e32 v155, v155
	v_exp_f32_e32 v166, v166
	v_exp_f32_e32 v167, v167
	v_pk_add_f32 v[128:129], v[128:129], 1.0 op_sel_hi:[1,0]
	v_pk_add_f32 v[156:157], v[156:157], 1.0 op_sel_hi:[1,0]
	v_pk_add_f32 v[130:131], v[130:131], 1.0 op_sel_hi:[1,0]
	v_pk_add_f32 v[158:159], v[158:159], 1.0 op_sel_hi:[1,0]
	v_pk_add_f32 v[152:153], v[152:153], 1.0 op_sel_hi:[1,0]
	v_pk_add_f32 v[160:161], v[160:161], 1.0 op_sel_hi:[1,0]
	v_pk_add_f32 v[154:155], v[154:155], 1.0 op_sel_hi:[1,0]
	v_pk_add_f32 v[166:167], v[166:167], 1.0 op_sel_hi:[1,0]
	v_rcp_f32_e32 v128, v128
	v_rcp_f32_e32 v129, v129
	v_rcp_f32_e32 v130, v130
	v_rcp_f32_e32 v131, v131
	v_rcp_f32_e32 v152, v152
	v_rcp_f32_e32 v153, v153
	v_rcp_f32_e32 v154, v154
	v_rcp_f32_e32 v155, v155
	v_pk_mul_f32 v[128:129], v[128:129], v[156:157]
	v_pk_mul_f32 v[130:131], v[130:131], v[158:159]
	v_pk_mul_f32 v[152:153], v[152:153], v[160:161]
	v_pk_mul_f32 v[154:155], v[154:155], v[166:167]
	v_pk_mul_f32 v[116:117], v[116:117], v[128:129]
	v_pk_mul_f32 v[118:119], v[118:119], v[130:131]
	v_pk_mul_f32 v[112:113], v[112:113], v[152:153]
	v_pk_mul_f32 v[114:115], v[114:115], v[154:155]
	v_lshlrev_b32_e32 v128, 16, v220
	v_and_b32_e32 v129, 0xffff0000, v220
	v_lshlrev_b32_e32 v156, 16, v228
	v_and_b32_e32 v157, 0xffff0000, v228
	v_lshlrev_b32_e32 v130, 16, v221
	v_and_b32_e32 v131, 0xffff0000, v221
	v_lshlrev_b32_e32 v158, 16, v229
	v_and_b32_e32 v159, 0xffff0000, v229
	v_lshlrev_b32_e32 v152, 16, v222
	v_and_b32_e32 v153, 0xffff0000, v222
	v_lshlrev_b32_e32 v160, 16, v230
	v_and_b32_e32 v161, 0xffff0000, v230
	v_lshlrev_b32_e32 v154, 16, v223
	v_and_b32_e32 v155, 0xffff0000, v223
	v_lshlrev_b32_e32 v166, 16, v231
	v_and_b32_e32 v167, 0xffff0000, v231
	v_pk_mul_f32 v[128:129], v[128:129], s[18:19]
	v_pk_mul_f32 v[156:157], v[156:157], s[18:19]
	v_pk_mul_f32 v[130:131], v[130:131], s[18:19]
	v_pk_mul_f32 v[158:159], v[158:159], s[18:19]
	v_pk_mul_f32 v[152:153], v[152:153], s[18:19]
	v_pk_mul_f32 v[160:161], v[160:161], s[18:19]
	v_pk_mul_f32 v[154:155], v[154:155], s[18:19]
	v_pk_mul_f32 v[166:167], v[166:167], s[18:19]
	v_exp_f32_e32 v128, v128
	v_exp_f32_e32 v129, v129
	v_exp_f32_e32 v156, v156
	v_exp_f32_e32 v157, v157
	v_exp_f32_e32 v130, v130
	v_exp_f32_e32 v131, v131
	v_exp_f32_e32 v158, v158
	v_exp_f32_e32 v159, v159
	v_exp_f32_e32 v152, v152
	v_exp_f32_e32 v153, v153
	v_exp_f32_e32 v160, v160
	v_exp_f32_e32 v161, v161
	v_exp_f32_e32 v154, v154
	v_exp_f32_e32 v155, v155
	v_exp_f32_e32 v166, v166
	v_exp_f32_e32 v167, v167
	v_pk_add_f32 v[128:129], v[128:129], 1.0 op_sel_hi:[1,0]
	v_pk_add_f32 v[156:157], v[156:157], 1.0 op_sel_hi:[1,0]
	v_pk_add_f32 v[130:131], v[130:131], 1.0 op_sel_hi:[1,0]
	v_pk_add_f32 v[158:159], v[158:159], 1.0 op_sel_hi:[1,0]
	v_pk_add_f32 v[152:153], v[152:153], 1.0 op_sel_hi:[1,0]
	v_pk_add_f32 v[160:161], v[160:161], 1.0 op_sel_hi:[1,0]
	v_pk_add_f32 v[154:155], v[154:155], 1.0 op_sel_hi:[1,0]
	v_pk_add_f32 v[166:167], v[166:167], 1.0 op_sel_hi:[1,0]
	v_rcp_f32_e32 v128, v128
	v_rcp_f32_e32 v129, v129
	v_rcp_f32_e32 v130, v130
	v_rcp_f32_e32 v131, v131
	v_rcp_f32_e32 v152, v152
	v_rcp_f32_e32 v153, v153
	v_rcp_f32_e32 v154, v154
	v_rcp_f32_e32 v155, v155
	v_pk_mul_f32 v[128:129], v[128:129], v[156:157]
	v_pk_mul_f32 v[130:131], v[130:131], v[158:159]
	v_pk_mul_f32 v[152:153], v[152:153], v[160:161]
	v_pk_mul_f32 v[154:155], v[154:155], v[166:167]
	v_pk_mul_f32 v[84:85], v[84:85], v[128:129]
	v_pk_mul_f32 v[86:87], v[86:87], v[130:131]
	v_pk_mul_f32 v[80:81], v[80:81], v[152:153]
	v_pk_mul_f32 v[82:83], v[82:83], v[154:155]
	global_load_dwordx4 v[196:199], v[218:219], off
	global_load_dwordx4 v[224:227], v[218:219], off offset:2048
	global_load_dwordx4 v[220:223], v[218:219], off offset:256
	global_load_dwordx4 v[228:231], v[218:219], off offset:2304
	v_lshl_add_u64 v[218:219], v[218:219], 0, s[20:21]
	s_waitcnt vmcnt(8)
; DEV float bflo(unsigned w) { return __uint_as_float(w << 16); }
; DEV float bfhi(unsigned w) { return __uint_as_float(w & 0xffff0000u); }
; #define RS_(xa, xb) ((1.0f + one * __expf(-(xb))) * __builtin_amdgcn_rcpf(1.0f + __expf(-(xa))))
;   DEV bool rescale(f32x4 (&acc)[2][2][4][2], const Unit& u, int wr, int wc, int fr, int fq) const {
;     ...
;     for (int ai = 0; ai < 2; ++ai)
; #pragma unroll
;       for (int m = 0; m < 4; ++m) {
;         const size_t r = (size_t)(row0 + ai * HALF + m * 16);
; #pragma unroll
;         for (int bj = 0; bj < 2; ++bj) {
;           const int c = col0 + bj * HALF;
;           const u32x4 ga = *(const u32x4*)(Z + r * NIN + GT + u.seg * D + c);
;           const u32x4 gb = *(const u32x4*)(Z + r * NIN + GT + sb * D + c);
;     ...
;           acc[ai][bj][m][0][0] *= RS_(bflo(ga.x), bflo(gb.x)); acc[ai][bj][m][0][1] *= RS_(bfhi(ga.x), bfhi(gb.x));
;           acc[ai][bj][m][0][2] *= RS_(bflo(ga.y), bflo(gb.y)); acc[ai][bj][m][0][3] *= RS_(bfhi(ga.y), bfhi(gb.y));
;           acc[ai][bj][m][1][0] *= RS_(bflo(ga.z), bflo(gb.z)); acc[ai][bj][m][1][1] *= RS_(bfhi(ga.z), bfhi(gb.z));
;           acc[ai][bj][m][1][2] *= RS_(bflo(ga.w), bflo(gb.w)); acc[ai][bj][m][1][3] *= RS_(bfhi(ga.w), bfhi(gb.w));
;     ...
;           asm volatile("" ::: "memory");
;         }
	v_lshlrev_b32_e32 v128, 16, v232
	v_and_b32_e32 v129, 0xffff0000, v232
	v_lshlrev_b32_e32 v156, 16, v240
	v_and_b32_e32 v157, 0xffff0000, v240
	v_lshlrev_b32_e32 v130, 16, v233
	v_and_b32_e32 v131, 0xffff0000, v233
	v_lshlrev_b32_e32 v158, 16, v241
	v_and_b32_e32 v159, 0xffff0000, v241
	v_lshlrev_b32_e32 v152, 16, v234
	v_and_b32_e32 v153, 0xffff0000, v234
	v_lshlrev_b32_e32 v160, 16, v242
	v_and_b32_e32 v161, 0xffff0000, v242
	v_lshlrev_b32_e32 v154, 16, v235
	v_and_b32_e32 v155, 0xffff0000, v235
	v_lshlrev_b32_e32 v166, 16, v243
	v_and_b32_e32 v167, 0xffff0000, v243
	v_pk_mul_f32 v[128:129], v[128:129], s[18:19]
	v_pk_mul_f32 v[156:157], v[156:157], s[18:19]
	v_pk_mul_f32 v[130:131], v[130:131], s[18:19]
	v_pk_mul_f32 v[158:159], v[158:159], s[18:19]
	v_pk_mul_f32 v[152:153], v[152:153], s[18:19]
	v_pk_mul_f32 v[160:161], v[160:161], s[18:19]
	v_pk_mul_f32 v[154:155], v[154:155], s[18:19]
	v_pk_mul_f32 v[166:167], v[166:167], s[18:19]
	v_exp_f32_e32 v128, v128
	v_exp_f32_e32 v129, v129
	v_exp_f32_e32 v156, v156
	v_exp_f32_e32 v157, v157
	v_exp_f32_e32 v130, v130
	v_exp_f32_e32 v131, v131
	v_exp_f32_e32 v158, v158
	v_exp_f32_e32 v159, v159
	v_exp_f32_e32 v152, v152
	v_exp_f32_e32 v153, v153
	v_exp_f32_e32 v160, v160
	v_exp_f32_e32 v161, v161
	v_exp_f32_e32 v154, v154
	v_exp_f32_e32 v155, v155
	v_exp_f32_e32 v166, v166
	v_exp_f32_e32 v167, v167
	v_pk_add_f32 v[128:129], v[128:129], 1.0 op_sel_hi:[1,0]
	v_pk_add_f32 v[156:157], v[156:157], 1.0 op_sel_hi:[1,0]
	v_pk_add_f32 v[130:131], v[130:131], 1.0 op_sel_hi:[1,0]
	v_pk_add_f32 v[158:159], v[158:159], 1.0 op_sel_hi:[1,0]
	v_pk_add_f32 v[152:153], v[152:153], 1.0 op_sel_hi:[1,0]
	v_pk_add_f32 v[160:161], v[160:161], 1.0 op_sel_hi:[1,0]
	v_pk_add_f32 v[154:155], v[154:155], 1.0 op_sel_hi:[1,0]
	v_pk_add_f32 v[166:167], v[166:167], 1.0 op_sel_hi:[1,0]
	v_rcp_f32_e32 v128, v128
	v_rcp_f32_e32 v129, v129
	v_rcp_f32_e32 v130, v130
	v_rcp_f32_e32 v131, v131
	v_rcp_f32_e32 v152, v152
	v_rcp_f32_e32 v153, v153
	v_rcp_f32_e32 v154, v154
	v_rcp_f32_e32 v155, v155
	v_pk_mul_f32 v[128:129], v[128:129], v[156:157]
	v_pk_mul_f32 v[130:131], v[130:131], v[158:159]
	v_pk_mul_f32 v[152:153], v[152:153], v[160:161]
	v_pk_mul_f32 v[154:155], v[154:155], v[166:167]
	v_pk_mul_f32 v[108:109], v[108:109], v[128:129]
	v_pk_mul_f32 v[110:111], v[110:111], v[130:131]
	v_pk_mul_f32 v[104:105], v[104:105], v[152:153]
	v_pk_mul_f32 v[106:107], v[106:107], v[154:155]
	v_lshlrev_b32_e32 v128, 16, v236
	v_and_b32_e32 v129, 0xffff0000, v236
	v_lshlrev_b32_e32 v156, 16, v148
	v_and_b32_e32 v157, 0xffff0000, v148
	v_lshlrev_b32_e32 v130, 16, v237
	v_and_b32_e32 v131, 0xffff0000, v237
	v_lshlrev_b32_e32 v158, 16, v149
	v_and_b32_e32 v159, 0xffff0000, v149
	v_lshlrev_b32_e32 v152, 16, v238
	v_and_b32_e32 v153, 0xffff0000, v238
	v_lshlrev_b32_e32 v160, 16, v150
	v_and_b32_e32 v161, 0xffff0000, v150
	v_lshlrev_b32_e32 v154, 16, v239
	v_and_b32_e32 v155, 0xffff0000, v239
	v_lshlrev_b32_e32 v166, 16, v151
	v_and_b32_e32 v167, 0xffff0000, v151
	v_pk_mul_f32 v[128:129], v[128:129], s[18:19]
	v_pk_mul_f32 v[156:157], v[156:157], s[18:19]
	v_pk_mul_f32 v[130:131], v[130:131], s[18:19]
	v_pk_mul_f32 v[158:159], v[158:159], s[18:19]
	v_pk_mul_f32 v[152:153], v[152:153], s[18:19]
	v_pk_mul_f32 v[160:161], v[160:161], s[18:19]
	v_pk_mul_f32 v[154:155], v[154:155], s[18:19]
	v_pk_mul_f32 v[166:167], v[166:167], s[18:19]
	v_exp_f32_e32 v128, v128
	v_exp_f32_e32 v129, v129
	v_exp_f32_e32 v156, v156
	v_exp_f32_e32 v157, v157
	v_exp_f32_e32 v130, v130
	v_exp_f32_e32 v131, v131
	v_exp_f32_e32 v158, v158
	v_exp_f32_e32 v159, v159
	v_exp_f32_e32 v152, v152
	v_exp_f32_e32 v153, v153
	v_exp_f32_e32 v160, v160
	v_exp_f32_e32 v161, v161
	v_exp_f32_e32 v154, v154
	v_exp_f32_e32 v155, v155
	v_exp_f32_e32 v166, v166
	v_exp_f32_e32 v167, v167
	v_pk_add_f32 v[128:129], v[128:129], 1.0 op_sel_hi:[1,0]
	v_pk_add_f32 v[156:157], v[156:157], 1.0 op_sel_hi:[1,0]
	v_pk_add_f32 v[130:131], v[130:131], 1.0 op_sel_hi:[1,0]
	v_pk_add_f32 v[158:159], v[158:159], 1.0 op_sel_hi:[1,0]
	v_pk_add_f32 v[152:153], v[152:153], 1.0 op_sel_hi:[1,0]
	v_pk_add_f32 v[160:161], v[160:161], 1.0 op_sel_hi:[1,0]
	v_pk_add_f32 v[154:155], v[154:155], 1.0 op_sel_hi:[1,0]
	v_pk_add_f32 v[166:167], v[166:167], 1.0 op_sel_hi:[1,0]
	v_rcp_f32_e32 v128, v128
	v_rcp_f32_e32 v129, v129
	v_rcp_f32_e32 v130, v130
	v_rcp_f32_e32 v131, v131
	v_rcp_f32_e32 v152, v152
	v_rcp_f32_e32 v153, v153
	v_rcp_f32_e32 v154, v154
	v_rcp_f32_e32 v155, v155
	v_pk_mul_f32 v[128:129], v[128:129], v[156:157]
	v_pk_mul_f32 v[130:131], v[130:131], v[158:159]
	v_pk_mul_f32 v[152:153], v[152:153], v[160:161]
	v_pk_mul_f32 v[154:155], v[154:155], v[166:167]
	v_pk_mul_f32 v[76:77], v[76:77], v[128:129]
	v_pk_mul_f32 v[78:79], v[78:79], v[130:131]
	v_pk_mul_f32 v[72:73], v[72:73], v[152:153]
	v_pk_mul_f32 v[74:75], v[74:75], v[154:155]
	global_load_dwordx4 v[232:235], v[218:219], off
	global_load_dwordx4 v[240:243], v[218:219], off offset:2048
	global_load_dwordx4 v[236:239], v[218:219], off offset:256
	global_load_dwordx4 v[148:151], v[218:219], off offset:2304
	v_lshl_add_u64 v[218:219], v[218:219], 0, s[20:21]
	s_waitcnt vmcnt(8)
; DEV float bflo(unsigned w) { return __uint_as_float(w << 16); }
; DEV float bfhi(unsigned w) { return __uint_as_float(w & 0xffff0000u); }
; #define RS_(xa, xb) ((1.0f + one * __expf(-(xb))) * __builtin_amdgcn_rcpf(1.0f + __expf(-(xa))))
;   DEV bool rescale(f32x4 (&acc)[2][2][4][2], const Unit& u, int wr, int wc, int fr, int fq) const {
;     ...
;     for (int ai = 0; ai < 2; ++ai)
; #pragma unroll
;       for (int m = 0; m < 4; ++m) {
;         const size_t r = (size_t)(row0 + ai * HALF + m * 16);
; #pragma unroll
;         for (int bj = 0; bj < 2; ++bj) {
;           const int c = col0 + bj * HALF;
;           const u32x4 ga = *(const u32x4*)(Z + r * NIN + GT + u.seg * D + c);
;           const u32x4 gb = *(const u32x4*)(Z + r * NIN + GT + sb * D + c);
;     ...
;           acc[ai][bj][m][0][0] *= RS_(bflo(ga.x), bflo(gb.x)); acc[ai][bj][m][0][1] *= RS_(bfhi(ga.x), bfhi(gb.x));
;           acc[ai][bj][m][0][2] *= RS_(bflo(ga.y), bflo(gb.y)); acc[ai][bj][m][0][3] *= RS_(bfhi(ga.y), bfhi(gb.y));
;           acc[ai][bj][m][1][0] *= RS_(bflo(ga.z), bflo(gb.z)); acc[ai][bj][m][1][1] *= RS_(bfhi(ga.z), bfhi(gb.z));
;           acc[ai][bj][m][1][2] *= RS_(bflo(ga.w), bflo(gb.w)); acc[ai][bj][m][1][3] *= RS_(bfhi(ga.w), bfhi(gb.w));
;     ...
;           asm volatile("" ::: "memory");
;         }
	v_lshlrev_b32_e32 v128, 16, v180
	v_and_b32_e32 v129, 0xffff0000, v180
	v_lshlrev_b32_e32 v156, 16, v188
	v_and_b32_e32 v157, 0xffff0000, v188
	v_lshlrev_b32_e32 v130, 16, v181
	v_and_b32_e32 v131, 0xffff0000, v181
	v_lshlrev_b32_e32 v158, 16, v189
	v_and_b32_e32 v159, 0xffff0000, v189
	v_lshlrev_b32_e32 v152, 16, v182
	v_and_b32_e32 v153, 0xffff0000, v182
	v_lshlrev_b32_e32 v160, 16, v190
	v_and_b32_e32 v161, 0xffff0000, v190
	v_lshlrev_b32_e32 v154, 16, v183
	v_and_b32_e32 v155, 0xffff0000, v183
	v_lshlrev_b32_e32 v166, 16, v191
	v_and_b32_e32 v167, 0xffff0000, v191
	v_pk_mul_f32 v[128:129], v[128:129], s[18:19]
	v_pk_mul_f32 v[156:157], v[156:157], s[18:19]
	v_pk_mul_f32 v[130:131], v[130:131], s[18:19]
	v_pk_mul_f32 v[158:159], v[158:159], s[18:19]
	v_pk_mul_f32 v[152:153], v[152:153], s[18:19]
	v_pk_mul_f32 v[160:161], v[160:161], s[18:19]
	v_pk_mul_f32 v[154:155], v[154:155], s[18:19]
	v_pk_mul_f32 v[166:167], v[166:167], s[18:19]
	v_exp_f32_e32 v128, v128
	v_exp_f32_e32 v129, v129
	v_exp_f32_e32 v156, v156
	v_exp_f32_e32 v157, v157
	v_exp_f32_e32 v130, v130
	v_exp_f32_e32 v131, v131
	v_exp_f32_e32 v158, v158
	v_exp_f32_e32 v159, v159
	v_exp_f32_e32 v152, v152
	v_exp_f32_e32 v153, v153
	v_exp_f32_e32 v160, v160
	v_exp_f32_e32 v161, v161
	v_exp_f32_e32 v154, v154
	v_exp_f32_e32 v155, v155
	v_exp_f32_e32 v166, v166
	v_exp_f32_e32 v167, v167
	v_pk_add_f32 v[128:129], v[128:129], 1.0 op_sel_hi:[1,0]
	v_pk_add_f32 v[156:157], v[156:157], 1.0 op_sel_hi:[1,0]
	v_pk_add_f32 v[130:131], v[130:131], 1.0 op_sel_hi:[1,0]
	v_pk_add_f32 v[158:159], v[158:159], 1.0 op_sel_hi:[1,0]
	v_pk_add_f32 v[152:153], v[152:153], 1.0 op_sel_hi:[1,0]
	v_pk_add_f32 v[160:161], v[160:161], 1.0 op_sel_hi:[1,0]
	v_pk_add_f32 v[154:155], v[154:155], 1.0 op_sel_hi:[1,0]
	v_pk_add_f32 v[166:167], v[166:167], 1.0 op_sel_hi:[1,0]
	v_rcp_f32_e32 v128, v128
	v_rcp_f32_e32 v129, v129
	v_rcp_f32_e32 v130, v130
	v_rcp_f32_e32 v131, v131
	v_rcp_f32_e32 v152, v152
	v_rcp_f32_e32 v153, v153
	v_rcp_f32_e32 v154, v154
	v_rcp_f32_e32 v155, v155
	v_pk_mul_f32 v[128:129], v[128:129], v[156:157]
	v_pk_mul_f32 v[130:131], v[130:131], v[158:159]
	v_pk_mul_f32 v[152:153], v[152:153], v[160:161]
	v_pk_mul_f32 v[154:155], v[154:155], v[166:167]
	v_pk_mul_f32 v[100:101], v[100:101], v[128:129]
	v_pk_mul_f32 v[102:103], v[102:103], v[130:131]
	v_pk_mul_f32 v[96:97], v[96:97], v[152:153]
	v_pk_mul_f32 v[98:99], v[98:99], v[154:155]
	v_lshlrev_b32_e32 v128, 16, v184
	v_and_b32_e32 v129, 0xffff0000, v184
	v_lshlrev_b32_e32 v156, 16, v192
	v_and_b32_e32 v157, 0xffff0000, v192
	v_lshlrev_b32_e32 v130, 16, v185
	v_and_b32_e32 v131, 0xffff0000, v185
	v_lshlrev_b32_e32 v158, 16, v193
	v_and_b32_e32 v159, 0xffff0000, v193
	v_lshlrev_b32_e32 v152, 16, v186
	v_and_b32_e32 v153, 0xffff0000, v186
	v_lshlrev_b32_e32 v160, 16, v194
	v_and_b32_e32 v161, 0xffff0000, v194
	v_lshlrev_b32_e32 v154, 16, v187
	v_and_b32_e32 v155, 0xffff0000, v187
	v_lshlrev_b32_e32 v166, 16, v195
	v_and_b32_e32 v167, 0xffff0000, v195
	v_pk_mul_f32 v[128:129], v[128:129], s[18:19]
	v_pk_mul_f32 v[156:157], v[156:157], s[18:19]
	v_pk_mul_f32 v[130:131], v[130:131], s[18:19]
	v_pk_mul_f32 v[158:159], v[158:159], s[18:19]
	v_pk_mul_f32 v[152:153], v[152:153], s[18:19]
	v_pk_mul_f32 v[160:161], v[160:161], s[18:19]
	v_pk_mul_f32 v[154:155], v[154:155], s[18:19]
	v_pk_mul_f32 v[166:167], v[166:167], s[18:19]
	v_exp_f32_e32 v128, v128
	v_exp_f32_e32 v129, v129
	v_exp_f32_e32 v156, v156
	v_exp_f32_e32 v157, v157
	v_exp_f32_e32 v130, v130
	v_exp_f32_e32 v131, v131
	v_exp_f32_e32 v158, v158
	v_exp_f32_e32 v159, v159
	v_exp_f32_e32 v152, v152
	v_exp_f32_e32 v153, v153
	v_exp_f32_e32 v160, v160
	v_exp_f32_e32 v161, v161
	v_exp_f32_e32 v154, v154
	v_exp_f32_e32 v155, v155
	v_exp_f32_e32 v166, v166
	v_exp_f32_e32 v167, v167
	v_pk_add_f32 v[128:129], v[128:129], 1.0 op_sel_hi:[1,0]
	v_pk_add_f32 v[156:157], v[156:157], 1.0 op_sel_hi:[1,0]
	v_pk_add_f32 v[130:131], v[130:131], 1.0 op_sel_hi:[1,0]
	v_pk_add_f32 v[158:159], v[158:159], 1.0 op_sel_hi:[1,0]
	v_pk_add_f32 v[152:153], v[152:153], 1.0 op_sel_hi:[1,0]
	v_pk_add_f32 v[160:161], v[160:161], 1.0 op_sel_hi:[1,0]
	v_pk_add_f32 v[154:155], v[154:155], 1.0 op_sel_hi:[1,0]
	v_pk_add_f32 v[166:167], v[166:167], 1.0 op_sel_hi:[1,0]
	v_rcp_f32_e32 v128, v128
	v_rcp_f32_e32 v129, v129
	v_rcp_f32_e32 v130, v130
	v_rcp_f32_e32 v131, v131
	v_rcp_f32_e32 v152, v152
	v_rcp_f32_e32 v153, v153
	v_rcp_f32_e32 v154, v154
	v_rcp_f32_e32 v155, v155
	v_pk_mul_f32 v[128:129], v[128:129], v[156:157]
	v_pk_mul_f32 v[130:131], v[130:131], v[158:159]
	v_pk_mul_f32 v[152:153], v[152:153], v[160:161]
	v_pk_mul_f32 v[154:155], v[154:155], v[166:167]
	v_pk_mul_f32 v[68:69], v[68:69], v[128:129]
	v_pk_mul_f32 v[70:71], v[70:71], v[130:131]
	v_pk_mul_f32 v[64:65], v[64:65], v[152:153]
	v_pk_mul_f32 v[66:67], v[66:67], v[154:155]
	global_load_dwordx4 v[180:183], v[218:219], off
	global_load_dwordx4 v[188:191], v[218:219], off offset:2048
	global_load_dwordx4 v[184:187], v[218:219], off offset:256
	global_load_dwordx4 v[192:195], v[218:219], off offset:2304
	v_lshl_add_u64 v[218:219], v[218:219], 0, s[20:21]
	s_waitcnt vmcnt(8)
; DEV float bflo(unsigned w) { return __uint_as_float(w << 16); }
; DEV float bfhi(unsigned w) { return __uint_as_float(w & 0xffff0000u); }
; #define RS_(xa, xb) ((1.0f + one * __expf(-(xb))) * __builtin_amdgcn_rcpf(1.0f + __expf(-(xa))))
;   DEV bool rescale(f32x4 (&acc)[2][2][4][2], const Unit& u, int wr, int wc, int fr, int fq) const {
;     ...
;     for (int ai = 0; ai < 2; ++ai)
; #pragma unroll
;       for (int m = 0; m < 4; ++m) {
;         const size_t r = (size_t)(row0 + ai * HALF + m * 16);
; #pragma unroll
;         for (int bj = 0; bj < 2; ++bj) {
;           const int c = col0 + bj * HALF;
;           const u32x4 ga = *(const u32x4*)(Z + r * NIN + GT + u.seg * D + c);
;           const u32x4 gb = *(const u32x4*)(Z + r * NIN + GT + sb * D + c);
;     ...
;           acc[ai][bj][m][0][0] *= RS_(bflo(ga.x), bflo(gb.x)); acc[ai][bj][m][0][1] *= RS_(bfhi(ga.x), bfhi(gb.x));
;           acc[ai][bj][m][0][2] *= RS_(bflo(ga.y), bflo(gb.y)); acc[ai][bj][m][0][3] *= RS_(bfhi(ga.y), bfhi(gb.y));
;           acc[ai][bj][m][1][0] *= RS_(bflo(ga.z), bflo(gb.z)); acc[ai][bj][m][1][1] *= RS_(bfhi(ga.z), bfhi(gb.z));
;           acc[ai][bj][m][1][2] *= RS_(bflo(ga.w), bflo(gb.w)); acc[ai][bj][m][1][3] *= RS_(bfhi(ga.w), bfhi(gb.w));
;     ...
;           asm volatile("" ::: "memory");
;         }
	v_lshlrev_b32_e32 v128, 16, v196
	v_and_b32_e32 v129, 0xffff0000, v196
	v_lshlrev_b32_e32 v156, 16, v224
	v_and_b32_e32 v157, 0xffff0000, v224
	v_lshlrev_b32_e32 v130, 16, v197
	v_and_b32_e32 v131, 0xffff0000, v197
	v_lshlrev_b32_e32 v158, 16, v225
	v_and_b32_e32 v159, 0xffff0000, v225
	v_lshlrev_b32_e32 v152, 16, v198
	v_and_b32_e32 v153, 0xffff0000, v198
	v_lshlrev_b32_e32 v160, 16, v226
	v_and_b32_e32 v161, 0xffff0000, v226
	v_lshlrev_b32_e32 v154, 16, v199
	v_and_b32_e32 v155, 0xffff0000, v199
	v_lshlrev_b32_e32 v166, 16, v227
	v_and_b32_e32 v167, 0xffff0000, v227
	v_pk_mul_f32 v[128:129], v[128:129], s[18:19]
	v_pk_mul_f32 v[156:157], v[156:157], s[18:19]
	v_pk_mul_f32 v[130:131], v[130:131], s[18:19]
	v_pk_mul_f32 v[158:159], v[158:159], s[18:19]
	v_pk_mul_f32 v[152:153], v[152:153], s[18:19]
	v_pk_mul_f32 v[160:161], v[160:161], s[18:19]
	v_pk_mul_f32 v[154:155], v[154:155], s[18:19]
	v_pk_mul_f32 v[166:167], v[166:167], s[18:19]
	v_exp_f32_e32 v128, v128
	v_exp_f32_e32 v129, v129
	v_exp_f32_e32 v156, v156
	v_exp_f32_e32 v157, v157
	v_exp_f32_e32 v130, v130
	v_exp_f32_e32 v131, v131
	v_exp_f32_e32 v158, v158
	v_exp_f32_e32 v159, v159
	v_exp_f32_e32 v152, v152
	v_exp_f32_e32 v153, v153
	v_exp_f32_e32 v160, v160
	v_exp_f32_e32 v161, v161
	v_exp_f32_e32 v154, v154
	v_exp_f32_e32 v155, v155
	v_exp_f32_e32 v166, v166
	v_exp_f32_e32 v167, v167
	v_pk_add_f32 v[128:129], v[128:129], 1.0 op_sel_hi:[1,0]
	v_pk_add_f32 v[156:157], v[156:157], 1.0 op_sel_hi:[1,0]
	v_pk_add_f32 v[130:131], v[130:131], 1.0 op_sel_hi:[1,0]
	v_pk_add_f32 v[158:159], v[158:159], 1.0 op_sel_hi:[1,0]
	v_pk_add_f32 v[152:153], v[152:153], 1.0 op_sel_hi:[1,0]
	v_pk_add_f32 v[160:161], v[160:161], 1.0 op_sel_hi:[1,0]
	v_pk_add_f32 v[154:155], v[154:155], 1.0 op_sel_hi:[1,0]
	v_pk_add_f32 v[166:167], v[166:167], 1.0 op_sel_hi:[1,0]
	v_rcp_f32_e32 v128, v128
	v_rcp_f32_e32 v129, v129
	v_rcp_f32_e32 v130, v130
	v_rcp_f32_e32 v131, v131
	v_rcp_f32_e32 v152, v152
	v_rcp_f32_e32 v153, v153
	v_rcp_f32_e32 v154, v154
	v_rcp_f32_e32 v155, v155
	v_pk_mul_f32 v[128:129], v[128:129], v[156:157]
	v_pk_mul_f32 v[130:131], v[130:131], v[158:159]
	v_pk_mul_f32 v[152:153], v[152:153], v[160:161]
	v_pk_mul_f32 v[154:155], v[154:155], v[166:167]
	v_pk_mul_f32 v[60:61], v[60:61], v[128:129]
	v_pk_mul_f32 v[62:63], v[62:63], v[130:131]
	v_pk_mul_f32 v[56:57], v[56:57], v[152:153]
	v_pk_mul_f32 v[58:59], v[58:59], v[154:155]
	v_lshlrev_b32_e32 v128, 16, v220
	v_and_b32_e32 v129, 0xffff0000, v220
	v_lshlrev_b32_e32 v156, 16, v228
	v_and_b32_e32 v157, 0xffff0000, v228
	v_lshlrev_b32_e32 v130, 16, v221
	v_and_b32_e32 v131, 0xffff0000, v221
	v_lshlrev_b32_e32 v158, 16, v229
	v_and_b32_e32 v159, 0xffff0000, v229
	v_lshlrev_b32_e32 v152, 16, v222
	v_and_b32_e32 v153, 0xffff0000, v222
	v_lshlrev_b32_e32 v160, 16, v230
	v_and_b32_e32 v161, 0xffff0000, v230
	v_lshlrev_b32_e32 v154, 16, v223
	v_and_b32_e32 v155, 0xffff0000, v223
	v_lshlrev_b32_e32 v166, 16, v231
	v_and_b32_e32 v167, 0xffff0000, v231
	v_pk_mul_f32 v[128:129], v[128:129], s[18:19]
	v_pk_mul_f32 v[156:157], v[156:157], s[18:19]
	v_pk_mul_f32 v[130:131], v[130:131], s[18:19]
	v_pk_mul_f32 v[158:159], v[158:159], s[18:19]
	v_pk_mul_f32 v[152:153], v[152:153], s[18:19]
	v_pk_mul_f32 v[160:161], v[160:161], s[18:19]
	v_pk_mul_f32 v[154:155], v[154:155], s[18:19]
	v_pk_mul_f32 v[166:167], v[166:167], s[18:19]
	v_exp_f32_e32 v128, v128
	v_exp_f32_e32 v129, v129
	v_exp_f32_e32 v156, v156
	v_exp_f32_e32 v157, v157
	v_exp_f32_e32 v130, v130
	v_exp_f32_e32 v131, v131
	v_exp_f32_e32 v158, v158
	v_exp_f32_e32 v159, v159
	v_exp_f32_e32 v152, v152
	v_exp_f32_e32 v153, v153
	v_exp_f32_e32 v160, v160
	v_exp_f32_e32 v161, v161
	v_exp_f32_e32 v154, v154
	v_exp_f32_e32 v155, v155
	v_exp_f32_e32 v166, v166
	v_exp_f32_e32 v167, v167
	v_pk_add_f32 v[128:129], v[128:129], 1.0 op_sel_hi:[1,0]
	v_pk_add_f32 v[156:157], v[156:157], 1.0 op_sel_hi:[1,0]
	v_pk_add_f32 v[130:131], v[130:131], 1.0 op_sel_hi:[1,0]
	v_pk_add_f32 v[158:159], v[158:159], 1.0 op_sel_hi:[1,0]
	v_pk_add_f32 v[152:153], v[152:153], 1.0 op_sel_hi:[1,0]
	v_pk_add_f32 v[160:161], v[160:161], 1.0 op_sel_hi:[1,0]
	v_pk_add_f32 v[154:155], v[154:155], 1.0 op_sel_hi:[1,0]
	v_pk_add_f32 v[166:167], v[166:167], 1.0 op_sel_hi:[1,0]
	v_rcp_f32_e32 v128, v128
	v_rcp_f32_e32 v129, v129
	v_rcp_f32_e32 v130, v130
	v_rcp_f32_e32 v131, v131
	v_rcp_f32_e32 v152, v152
	v_rcp_f32_e32 v153, v153
	v_rcp_f32_e32 v154, v154
	v_rcp_f32_e32 v155, v155
	v_pk_mul_f32 v[128:129], v[128:129], v[156:157]
	v_pk_mul_f32 v[130:131], v[130:131], v[158:159]
	v_pk_mul_f32 v[152:153], v[152:153], v[160:161]
	v_pk_mul_f32 v[154:155], v[154:155], v[166:167]
	v_pk_mul_f32 v[28:29], v[28:29], v[128:129]
	v_pk_mul_f32 v[30:31], v[30:31], v[130:131]
	v_pk_mul_f32 v[24:25], v[24:25], v[152:153]
	v_pk_mul_f32 v[26:27], v[26:27], v[154:155]
	global_load_dwordx4 v[196:199], v[218:219], off
	global_load_dwordx4 v[224:227], v[218:219], off offset:2048
	global_load_dwordx4 v[220:223], v[218:219], off offset:256
	global_load_dwordx4 v[228:231], v[218:219], off offset:2304
	s_waitcnt vmcnt(8)
; DEV float bflo(unsigned w) { return __uint_as_float(w << 16); }
; DEV float bfhi(unsigned w) { return __uint_as_float(w & 0xffff0000u); }
; #define RS_(xa, xb) ((1.0f + one * __expf(-(xb))) * __builtin_amdgcn_rcpf(1.0f + __expf(-(xa))))
;   DEV bool rescale(f32x4 (&acc)[2][2][4][2], const Unit& u, int wr, int wc, int fr, int fq) const {
;     ...
;     for (int ai = 0; ai < 2; ++ai)
; #pragma unroll
;       for (int m = 0; m < 4; ++m) {
;         const size_t r = (size_t)(row0 + ai * HALF + m * 16);
; #pragma unroll
;         for (int bj = 0; bj < 2; ++bj) {
;           const int c = col0 + bj * HALF;
;           const u32x4 ga = *(const u32x4*)(Z + r * NIN + GT + u.seg * D + c);
;           const u32x4 gb = *(const u32x4*)(Z + r * NIN + GT + sb * D + c);
;     ...
;           acc[ai][bj][m][0][0] *= RS_(bflo(ga.x), bflo(gb.x)); acc[ai][bj][m][0][1] *= RS_(bfhi(ga.x), bfhi(gb.x));
;           acc[ai][bj][m][0][2] *= RS_(bflo(ga.y), bflo(gb.y)); acc[ai][bj][m][0][3] *= RS_(bfhi(ga.y), bfhi(gb.y));
;           acc[ai][bj][m][1][0] *= RS_(bflo(ga.z), bflo(gb.z)); acc[ai][bj][m][1][1] *= RS_(bfhi(ga.z), bfhi(gb.z));
;           acc[ai][bj][m][1][2] *= RS_(bflo(ga.w), bflo(gb.w)); acc[ai][bj][m][1][3] *= RS_(bfhi(ga.w), bfhi(gb.w));
;     ...
;           asm volatile("" ::: "memory");
;         }
	v_lshlrev_b32_e32 v128, 16, v232
	v_and_b32_e32 v129, 0xffff0000, v232
	v_lshlrev_b32_e32 v156, 16, v240
	v_and_b32_e32 v157, 0xffff0000, v240
	v_lshlrev_b32_e32 v130, 16, v233
	v_and_b32_e32 v131, 0xffff0000, v233
	v_lshlrev_b32_e32 v158, 16, v241
	v_and_b32_e32 v159, 0xffff0000, v241
	v_lshlrev_b32_e32 v152, 16, v234
	v_and_b32_e32 v153, 0xffff0000, v234
	v_lshlrev_b32_e32 v160, 16, v242
	v_and_b32_e32 v161, 0xffff0000, v242
	v_lshlrev_b32_e32 v154, 16, v235
	v_and_b32_e32 v155, 0xffff0000, v235
	v_lshlrev_b32_e32 v166, 16, v243
	v_and_b32_e32 v167, 0xffff0000, v243
	v_pk_mul_f32 v[128:129], v[128:129], s[18:19]
	v_pk_mul_f32 v[156:157], v[156:157], s[18:19]
	v_pk_mul_f32 v[130:131], v[130:131], s[18:19]
	v_pk_mul_f32 v[158:159], v[158:159], s[18:19]
	v_pk_mul_f32 v[152:153], v[152:153], s[18:19]
	v_pk_mul_f32 v[160:161], v[160:161], s[18:19]
	v_pk_mul_f32 v[154:155], v[154:155], s[18:19]
	v_pk_mul_f32 v[166:167], v[166:167], s[18:19]
	v_exp_f32_e32 v128, v128
	v_exp_f32_e32 v129, v129
	v_exp_f32_e32 v156, v156
	v_exp_f32_e32 v157, v157
	v_exp_f32_e32 v130, v130
	v_exp_f32_e32 v131, v131
	v_exp_f32_e32 v158, v158
	v_exp_f32_e32 v159, v159
	v_exp_f32_e32 v152, v152
	v_exp_f32_e32 v153, v153
	v_exp_f32_e32 v160, v160
	v_exp_f32_e32 v161, v161
	v_exp_f32_e32 v154, v154
	v_exp_f32_e32 v155, v155
	v_exp_f32_e32 v166, v166
	v_exp_f32_e32 v167, v167
	v_pk_add_f32 v[128:129], v[128:129], 1.0 op_sel_hi:[1,0]
	v_pk_add_f32 v[156:157], v[156:157], 1.0 op_sel_hi:[1,0]
	v_pk_add_f32 v[130:131], v[130:131], 1.0 op_sel_hi:[1,0]
	v_pk_add_f32 v[158:159], v[158:159], 1.0 op_sel_hi:[1,0]
	v_pk_add_f32 v[152:153], v[152:153], 1.0 op_sel_hi:[1,0]
	v_pk_add_f32 v[160:161], v[160:161], 1.0 op_sel_hi:[1,0]
	v_pk_add_f32 v[154:155], v[154:155], 1.0 op_sel_hi:[1,0]
	v_pk_add_f32 v[166:167], v[166:167], 1.0 op_sel_hi:[1,0]
	v_rcp_f32_e32 v128, v128
	v_rcp_f32_e32 v129, v129
	v_rcp_f32_e32 v130, v130
	v_rcp_f32_e32 v131, v131
	v_rcp_f32_e32 v152, v152
	v_rcp_f32_e32 v153, v153
	v_rcp_f32_e32 v154, v154
	v_rcp_f32_e32 v155, v155
	v_pk_mul_f32 v[128:129], v[128:129], v[156:157]
	v_pk_mul_f32 v[130:131], v[130:131], v[158:159]
	v_pk_mul_f32 v[152:153], v[152:153], v[160:161]
	v_pk_mul_f32 v[154:155], v[154:155], v[166:167]
	v_pk_mul_f32 v[52:53], v[52:53], v[128:129]
	v_pk_mul_f32 v[54:55], v[54:55], v[130:131]
	v_pk_mul_f32 v[48:49], v[48:49], v[152:153]
	v_pk_mul_f32 v[50:51], v[50:51], v[154:155]
	v_lshlrev_b32_e32 v128, 16, v236
	v_and_b32_e32 v129, 0xffff0000, v236
	v_lshlrev_b32_e32 v156, 16, v148
	v_and_b32_e32 v157, 0xffff0000, v148
	v_lshlrev_b32_e32 v130, 16, v237
	v_and_b32_e32 v131, 0xffff0000, v237
	v_lshlrev_b32_e32 v158, 16, v149
	v_and_b32_e32 v159, 0xffff0000, v149
	v_lshlrev_b32_e32 v152, 16, v238
	v_and_b32_e32 v153, 0xffff0000, v238
	v_lshlrev_b32_e32 v160, 16, v150
	v_and_b32_e32 v161, 0xffff0000, v150
	v_lshlrev_b32_e32 v154, 16, v239
	v_and_b32_e32 v155, 0xffff0000, v239
	v_lshlrev_b32_e32 v166, 16, v151
	v_and_b32_e32 v167, 0xffff0000, v151
	v_pk_mul_f32 v[128:129], v[128:129], s[18:19]
	v_pk_mul_f32 v[156:157], v[156:157], s[18:19]
	v_pk_mul_f32 v[130:131], v[130:131], s[18:19]
	v_pk_mul_f32 v[158:159], v[158:159], s[18:19]
	v_pk_mul_f32 v[152:153], v[152:153], s[18:19]
	v_pk_mul_f32 v[160:161], v[160:161], s[18:19]
	v_pk_mul_f32 v[154:155], v[154:155], s[18:19]
	v_pk_mul_f32 v[166:167], v[166:167], s[18:19]
	v_exp_f32_e32 v128, v128
	v_exp_f32_e32 v129, v129
	v_exp_f32_e32 v156, v156
	v_exp_f32_e32 v157, v157
	v_exp_f32_e32 v130, v130
	v_exp_f32_e32 v131, v131
	v_exp_f32_e32 v158, v158
	v_exp_f32_e32 v159, v159
	v_exp_f32_e32 v152, v152
	v_exp_f32_e32 v153, v153
	v_exp_f32_e32 v160, v160
	v_exp_f32_e32 v161, v161
	v_exp_f32_e32 v154, v154
	v_exp_f32_e32 v155, v155
	v_exp_f32_e32 v166, v166
	v_exp_f32_e32 v167, v167
	v_pk_add_f32 v[128:129], v[128:129], 1.0 op_sel_hi:[1,0]
	v_pk_add_f32 v[156:157], v[156:157], 1.0 op_sel_hi:[1,0]
	v_pk_add_f32 v[130:131], v[130:131], 1.0 op_sel_hi:[1,0]
	v_pk_add_f32 v[158:159], v[158:159], 1.0 op_sel_hi:[1,0]
	v_pk_add_f32 v[152:153], v[152:153], 1.0 op_sel_hi:[1,0]
	v_pk_add_f32 v[160:161], v[160:161], 1.0 op_sel_hi:[1,0]
	v_pk_add_f32 v[154:155], v[154:155], 1.0 op_sel_hi:[1,0]
	v_pk_add_f32 v[166:167], v[166:167], 1.0 op_sel_hi:[1,0]
	v_rcp_f32_e32 v128, v128
	v_rcp_f32_e32 v129, v129
	v_rcp_f32_e32 v130, v130
	v_rcp_f32_e32 v131, v131
	v_rcp_f32_e32 v152, v152
	v_rcp_f32_e32 v153, v153
	v_rcp_f32_e32 v154, v154
	v_rcp_f32_e32 v155, v155
	v_pk_mul_f32 v[128:129], v[128:129], v[156:157]
	v_pk_mul_f32 v[130:131], v[130:131], v[158:159]
	v_pk_mul_f32 v[152:153], v[152:153], v[160:161]
	v_pk_mul_f32 v[154:155], v[154:155], v[166:167]
	v_pk_mul_f32 v[20:21], v[20:21], v[128:129]
	v_pk_mul_f32 v[22:23], v[22:23], v[130:131]
	v_pk_mul_f32 v[16:17], v[16:17], v[152:153]
	v_pk_mul_f32 v[18:19], v[18:19], v[154:155]
	s_waitcnt vmcnt(4)
; DEV float bflo(unsigned w) { return __uint_as_float(w << 16); }
; DEV float bfhi(unsigned w) { return __uint_as_float(w & 0xffff0000u); }
; #define RS_(xa, xb) ((1.0f + one * __expf(-(xb))) * __builtin_amdgcn_rcpf(1.0f + __expf(-(xa))))
;   DEV bool rescale(f32x4 (&acc)[2][2][4][2], const Unit& u, int wr, int wc, int fr, int fq) const {
;     ...
;     for (int ai = 0; ai < 2; ++ai)
; #pragma unroll
;       for (int m = 0; m < 4; ++m) {
;         const size_t r = (size_t)(row0 + ai * HALF + m * 16);
; #pragma unroll
;         for (int bj = 0; bj < 2; ++bj) {
;           const int c = col0 + bj * HALF;
;           const u32x4 ga = *(const u32x4*)(Z + r * NIN + GT + u.seg * D + c);
;           const u32x4 gb = *(const u32x4*)(Z + r * NIN + GT + sb * D + c);
;     ...
;           acc[ai][bj][m][0][0] *= RS_(bflo(ga.x), bflo(gb.x)); acc[ai][bj][m][0][1] *= RS_(bfhi(ga.x), bfhi(gb.x));
;           acc[ai][bj][m][0][2] *= RS_(bflo(ga.y), bflo(gb.y)); acc[ai][bj][m][0][3] *= RS_(bfhi(ga.y), bfhi(gb.y));
;           acc[ai][bj][m][1][0] *= RS_(bflo(ga.z), bflo(gb.z)); acc[ai][bj][m][1][1] *= RS_(bfhi(ga.z), bfhi(gb.z));
;           acc[ai][bj][m][1][2] *= RS_(bflo(ga.w), bflo(gb.w)); acc[ai][bj][m][1][3] *= RS_(bfhi(ga.w), bfhi(gb.w));
;     ...
;           asm volatile("" ::: "memory");
;         }
	v_lshlrev_b32_e32 v128, 16, v180
	v_and_b32_e32 v129, 0xffff0000, v180
	v_lshlrev_b32_e32 v156, 16, v188
	v_and_b32_e32 v157, 0xffff0000, v188
	v_lshlrev_b32_e32 v130, 16, v181
	v_and_b32_e32 v131, 0xffff0000, v181
	v_lshlrev_b32_e32 v158, 16, v189
	v_and_b32_e32 v159, 0xffff0000, v189
	v_lshlrev_b32_e32 v152, 16, v182
	v_and_b32_e32 v153, 0xffff0000, v182
	v_lshlrev_b32_e32 v160, 16, v190
	v_and_b32_e32 v161, 0xffff0000, v190
	v_lshlrev_b32_e32 v154, 16, v183
	v_and_b32_e32 v155, 0xffff0000, v183
	v_lshlrev_b32_e32 v166, 16, v191
	v_and_b32_e32 v167, 0xffff0000, v191
	v_pk_mul_f32 v[128:129], v[128:129], s[18:19]
	v_pk_mul_f32 v[156:157], v[156:157], s[18:19]
	v_pk_mul_f32 v[130:131], v[130:131], s[18:19]
	v_pk_mul_f32 v[158:159], v[158:159], s[18:19]
	v_pk_mul_f32 v[152:153], v[152:153], s[18:19]
	v_pk_mul_f32 v[160:161], v[160:161], s[18:19]
	v_pk_mul_f32 v[154:155], v[154:155], s[18:19]
	v_pk_mul_f32 v[166:167], v[166:167], s[18:19]
	v_exp_f32_e32 v128, v128
	v_exp_f32_e32 v129, v129
	v_exp_f32_e32 v156, v156
	v_exp_f32_e32 v157, v157
	v_exp_f32_e32 v130, v130
	v_exp_f32_e32 v131, v131
	v_exp_f32_e32 v158, v158
	v_exp_f32_e32 v159, v159
	v_exp_f32_e32 v152, v152
	v_exp_f32_e32 v153, v153
	v_exp_f32_e32 v160, v160
	v_exp_f32_e32 v161, v161
	v_exp_f32_e32 v154, v154
	v_exp_f32_e32 v155, v155
	v_exp_f32_e32 v166, v166
	v_exp_f32_e32 v167, v167
	v_pk_add_f32 v[128:129], v[128:129], 1.0 op_sel_hi:[1,0]
	v_pk_add_f32 v[156:157], v[156:157], 1.0 op_sel_hi:[1,0]
	v_pk_add_f32 v[130:131], v[130:131], 1.0 op_sel_hi:[1,0]
	v_pk_add_f32 v[158:159], v[158:159], 1.0 op_sel_hi:[1,0]
	v_pk_add_f32 v[152:153], v[152:153], 1.0 op_sel_hi:[1,0]
	v_pk_add_f32 v[160:161], v[160:161], 1.0 op_sel_hi:[1,0]
	v_pk_add_f32 v[154:155], v[154:155], 1.0 op_sel_hi:[1,0]
	v_pk_add_f32 v[166:167], v[166:167], 1.0 op_sel_hi:[1,0]
	v_rcp_f32_e32 v128, v128
	v_rcp_f32_e32 v129, v129
	v_rcp_f32_e32 v130, v130
	v_rcp_f32_e32 v131, v131
	v_rcp_f32_e32 v152, v152
	v_rcp_f32_e32 v153, v153
	v_rcp_f32_e32 v154, v154
	v_rcp_f32_e32 v155, v155
	v_pk_mul_f32 v[128:129], v[128:129], v[156:157]
	v_pk_mul_f32 v[130:131], v[130:131], v[158:159]
	v_pk_mul_f32 v[152:153], v[152:153], v[160:161]
	v_pk_mul_f32 v[154:155], v[154:155], v[166:167]
	v_pk_mul_f32 v[44:45], v[44:45], v[128:129]
	v_pk_mul_f32 v[46:47], v[46:47], v[130:131]
	v_pk_mul_f32 v[40:41], v[40:41], v[152:153]
	v_pk_mul_f32 v[42:43], v[42:43], v[154:155]
	v_lshlrev_b32_e32 v128, 16, v184
	v_and_b32_e32 v129, 0xffff0000, v184
	v_lshlrev_b32_e32 v156, 16, v192
	v_and_b32_e32 v157, 0xffff0000, v192
	v_lshlrev_b32_e32 v130, 16, v185
	v_and_b32_e32 v131, 0xffff0000, v185
	v_lshlrev_b32_e32 v158, 16, v193
	v_and_b32_e32 v159, 0xffff0000, v193
	v_lshlrev_b32_e32 v152, 16, v186
	v_and_b32_e32 v153, 0xffff0000, v186
	v_lshlrev_b32_e32 v160, 16, v194
	v_and_b32_e32 v161, 0xffff0000, v194
	v_lshlrev_b32_e32 v154, 16, v187
	v_and_b32_e32 v155, 0xffff0000, v187
	v_lshlrev_b32_e32 v166, 16, v195
	v_and_b32_e32 v167, 0xffff0000, v195
	v_pk_mul_f32 v[128:129], v[128:129], s[18:19]
	v_pk_mul_f32 v[156:157], v[156:157], s[18:19]
	v_pk_mul_f32 v[130:131], v[130:131], s[18:19]
	v_pk_mul_f32 v[158:159], v[158:159], s[18:19]
	v_pk_mul_f32 v[152:153], v[152:153], s[18:19]
	v_pk_mul_f32 v[160:161], v[160:161], s[18:19]
	v_pk_mul_f32 v[154:155], v[154:155], s[18:19]
	v_pk_mul_f32 v[166:167], v[166:167], s[18:19]
	v_exp_f32_e32 v128, v128
	v_exp_f32_e32 v129, v129
	v_exp_f32_e32 v156, v156
	v_exp_f32_e32 v157, v157
	v_exp_f32_e32 v130, v130
	v_exp_f32_e32 v131, v131
	v_exp_f32_e32 v158, v158
	v_exp_f32_e32 v159, v159
	v_exp_f32_e32 v152, v152
	v_exp_f32_e32 v153, v153
	v_exp_f32_e32 v160, v160
	v_exp_f32_e32 v161, v161
	v_exp_f32_e32 v154, v154
	v_exp_f32_e32 v155, v155
	v_exp_f32_e32 v166, v166
	v_exp_f32_e32 v167, v167
	v_pk_add_f32 v[128:129], v[128:129], 1.0 op_sel_hi:[1,0]
	v_pk_add_f32 v[156:157], v[156:157], 1.0 op_sel_hi:[1,0]
	v_pk_add_f32 v[130:131], v[130:131], 1.0 op_sel_hi:[1,0]
	v_pk_add_f32 v[158:159], v[158:159], 1.0 op_sel_hi:[1,0]
	v_pk_add_f32 v[152:153], v[152:153], 1.0 op_sel_hi:[1,0]
	v_pk_add_f32 v[160:161], v[160:161], 1.0 op_sel_hi:[1,0]
	v_pk_add_f32 v[154:155], v[154:155], 1.0 op_sel_hi:[1,0]
	v_pk_add_f32 v[166:167], v[166:167], 1.0 op_sel_hi:[1,0]
	v_rcp_f32_e32 v128, v128
	v_rcp_f32_e32 v129, v129
	v_rcp_f32_e32 v130, v130
	v_rcp_f32_e32 v131, v131
	v_rcp_f32_e32 v152, v152
	v_rcp_f32_e32 v153, v153
	v_rcp_f32_e32 v154, v154
	v_rcp_f32_e32 v155, v155
	v_pk_mul_f32 v[128:129], v[128:129], v[156:157]
	v_pk_mul_f32 v[130:131], v[130:131], v[158:159]
	v_pk_mul_f32 v[152:153], v[152:153], v[160:161]
	v_pk_mul_f32 v[154:155], v[154:155], v[166:167]
	v_pk_mul_f32 v[12:13], v[12:13], v[128:129]
	v_pk_mul_f32 v[14:15], v[14:15], v[130:131]
	v_pk_mul_f32 v[8:9], v[8:9], v[152:153]
	v_pk_mul_f32 v[10:11], v[10:11], v[154:155]
	s_waitcnt vmcnt(0)
; DEV float bflo(unsigned w) { return __uint_as_float(w << 16); }
; DEV float bfhi(unsigned w) { return __uint_as_float(w & 0xffff0000u); }
; #define RS_(xa, xb) ((1.0f + one * __expf(-(xb))) * __builtin_amdgcn_rcpf(1.0f + __expf(-(xa))))
;   DEV bool rescale(f32x4 (&acc)[2][2][4][2], const Unit& u, int wr, int wc, int fr, int fq) const {
;     ...
;     for (int ai = 0; ai < 2; ++ai)
; #pragma unroll
;       for (int m = 0; m < 4; ++m) {
;         const size_t r = (size_t)(row0 + ai * HALF + m * 16);
; #pragma unroll
;         for (int bj = 0; bj < 2; ++bj) {
;           const int c = col0 + bj * HALF;
;           const u32x4 ga = *(const u32x4*)(Z + r * NIN + GT + u.seg * D + c);
;           const u32x4 gb = *(const u32x4*)(Z + r * NIN + GT + sb * D + c);
;     ...
;           acc[ai][bj][m][0][0] *= RS_(bflo(ga.x), bflo(gb.x)); acc[ai][bj][m][0][1] *= RS_(bfhi(ga.x), bfhi(gb.x));
;           acc[ai][bj][m][0][2] *= RS_(bflo(ga.y), bflo(gb.y)); acc[ai][bj][m][0][3] *= RS_(bfhi(ga.y), bfhi(gb.y));
;           acc[ai][bj][m][1][0] *= RS_(bflo(ga.z), bflo(gb.z)); acc[ai][bj][m][1][1] *= RS_(bfhi(ga.z), bfhi(gb.z));
;           acc[ai][bj][m][1][2] *= RS_(bflo(ga.w), bflo(gb.w)); acc[ai][bj][m][1][3] *= RS_(bfhi(ga.w), bfhi(gb.w));
;     ...
;           asm volatile("" ::: "memory");
;         }
	v_lshlrev_b32_e32 v128, 16, v196
	v_and_b32_e32 v129, 0xffff0000, v196
	v_lshlrev_b32_e32 v156, 16, v224
	v_and_b32_e32 v157, 0xffff0000, v224
	v_lshlrev_b32_e32 v130, 16, v197
	v_and_b32_e32 v131, 0xffff0000, v197
	v_lshlrev_b32_e32 v158, 16, v225
	v_and_b32_e32 v159, 0xffff0000, v225
	v_lshlrev_b32_e32 v152, 16, v198
	v_and_b32_e32 v153, 0xffff0000, v198
	v_lshlrev_b32_e32 v160, 16, v226
	v_and_b32_e32 v161, 0xffff0000, v226
	v_lshlrev_b32_e32 v154, 16, v199
	v_and_b32_e32 v155, 0xffff0000, v199
	v_lshlrev_b32_e32 v166, 16, v227
	v_and_b32_e32 v167, 0xffff0000, v227
	v_pk_mul_f32 v[128:129], v[128:129], s[18:19]
	v_pk_mul_f32 v[156:157], v[156:157], s[18:19]
	v_pk_mul_f32 v[130:131], v[130:131], s[18:19]
	v_pk_mul_f32 v[158:159], v[158:159], s[18:19]
	v_pk_mul_f32 v[152:153], v[152:153], s[18:19]
	v_pk_mul_f32 v[160:161], v[160:161], s[18:19]
	v_pk_mul_f32 v[154:155], v[154:155], s[18:19]
	v_pk_mul_f32 v[166:167], v[166:167], s[18:19]
	v_exp_f32_e32 v128, v128
	v_exp_f32_e32 v129, v129
	v_exp_f32_e32 v156, v156
	v_exp_f32_e32 v157, v157
	v_exp_f32_e32 v130, v130
	v_exp_f32_e32 v131, v131
	v_exp_f32_e32 v158, v158
	v_exp_f32_e32 v159, v159
	v_exp_f32_e32 v152, v152
	v_exp_f32_e32 v153, v153
	v_exp_f32_e32 v160, v160
	v_exp_f32_e32 v161, v161
	v_exp_f32_e32 v154, v154
	v_exp_f32_e32 v155, v155
	v_exp_f32_e32 v166, v166
	v_exp_f32_e32 v167, v167
	v_pk_add_f32 v[128:129], v[128:129], 1.0 op_sel_hi:[1,0]
	v_pk_add_f32 v[156:157], v[156:157], 1.0 op_sel_hi:[1,0]
	v_pk_add_f32 v[130:131], v[130:131], 1.0 op_sel_hi:[1,0]
	v_pk_add_f32 v[158:159], v[158:159], 1.0 op_sel_hi:[1,0]
	v_pk_add_f32 v[152:153], v[152:153], 1.0 op_sel_hi:[1,0]
	v_pk_add_f32 v[160:161], v[160:161], 1.0 op_sel_hi:[1,0]
	v_pk_add_f32 v[154:155], v[154:155], 1.0 op_sel_hi:[1,0]
	v_pk_add_f32 v[166:167], v[166:167], 1.0 op_sel_hi:[1,0]
	v_rcp_f32_e32 v128, v128
	v_rcp_f32_e32 v129, v129
	v_rcp_f32_e32 v130, v130
	v_rcp_f32_e32 v131, v131
	v_rcp_f32_e32 v152, v152
	v_rcp_f32_e32 v153, v153
	v_rcp_f32_e32 v154, v154
	v_rcp_f32_e32 v155, v155
	v_pk_mul_f32 v[128:129], v[128:129], v[156:157]
	v_pk_mul_f32 v[130:131], v[130:131], v[158:159]
	v_pk_mul_f32 v[152:153], v[152:153], v[160:161]
	v_pk_mul_f32 v[154:155], v[154:155], v[166:167]
	v_pk_mul_f32 v[36:37], v[36:37], v[128:129]
	v_pk_mul_f32 v[38:39], v[38:39], v[130:131]
	v_pk_mul_f32 v[32:33], v[32:33], v[152:153]
	v_pk_mul_f32 v[34:35], v[34:35], v[154:155]
	v_lshlrev_b32_e32 v128, 16, v220
	v_and_b32_e32 v129, 0xffff0000, v220
	v_lshlrev_b32_e32 v156, 16, v228
	v_and_b32_e32 v157, 0xffff0000, v228
	v_lshlrev_b32_e32 v130, 16, v221
	v_and_b32_e32 v131, 0xffff0000, v221
	v_lshlrev_b32_e32 v158, 16, v229
	v_and_b32_e32 v159, 0xffff0000, v229
	v_lshlrev_b32_e32 v152, 16, v222
	v_and_b32_e32 v153, 0xffff0000, v222
	v_lshlrev_b32_e32 v160, 16, v230
	v_and_b32_e32 v161, 0xffff0000, v230
	v_lshlrev_b32_e32 v154, 16, v223
	v_and_b32_e32 v155, 0xffff0000, v223
	v_lshlrev_b32_e32 v166, 16, v231
	v_and_b32_e32 v167, 0xffff0000, v231
	v_pk_mul_f32 v[128:129], v[128:129], s[18:19]
	v_pk_mul_f32 v[156:157], v[156:157], s[18:19]
	v_pk_mul_f32 v[130:131], v[130:131], s[18:19]
	v_pk_mul_f32 v[158:159], v[158:159], s[18:19]
	v_pk_mul_f32 v[152:153], v[152:153], s[18:19]
	v_pk_mul_f32 v[160:161], v[160:161], s[18:19]
	v_pk_mul_f32 v[154:155], v[154:155], s[18:19]
	v_pk_mul_f32 v[166:167], v[166:167], s[18:19]
	v_exp_f32_e32 v128, v128
	v_exp_f32_e32 v129, v129
	v_exp_f32_e32 v156, v156
	v_exp_f32_e32 v157, v157
	v_exp_f32_e32 v130, v130
	v_exp_f32_e32 v131, v131
	v_exp_f32_e32 v158, v158
	v_exp_f32_e32 v159, v159
	v_exp_f32_e32 v152, v152
	v_exp_f32_e32 v153, v153
	v_exp_f32_e32 v160, v160
	v_exp_f32_e32 v161, v161
	v_exp_f32_e32 v154, v154
	v_exp_f32_e32 v155, v155
	v_exp_f32_e32 v166, v166
	v_exp_f32_e32 v167, v167
	v_pk_add_f32 v[128:129], v[128:129], 1.0 op_sel_hi:[1,0]
	v_pk_add_f32 v[156:157], v[156:157], 1.0 op_sel_hi:[1,0]
	v_pk_add_f32 v[130:131], v[130:131], 1.0 op_sel_hi:[1,0]
	v_pk_add_f32 v[158:159], v[158:159], 1.0 op_sel_hi:[1,0]
	v_pk_add_f32 v[152:153], v[152:153], 1.0 op_sel_hi:[1,0]
	v_pk_add_f32 v[160:161], v[160:161], 1.0 op_sel_hi:[1,0]
	v_pk_add_f32 v[154:155], v[154:155], 1.0 op_sel_hi:[1,0]
	v_pk_add_f32 v[166:167], v[166:167], 1.0 op_sel_hi:[1,0]
	v_rcp_f32_e32 v128, v128
	v_rcp_f32_e32 v129, v129
	v_rcp_f32_e32 v130, v130
	v_rcp_f32_e32 v131, v131
	v_rcp_f32_e32 v152, v152
	v_rcp_f32_e32 v153, v153
	v_rcp_f32_e32 v154, v154
	v_rcp_f32_e32 v155, v155
	v_pk_mul_f32 v[128:129], v[128:129], v[156:157]
	v_pk_mul_f32 v[130:131], v[130:131], v[158:159]
	v_pk_mul_f32 v[152:153], v[152:153], v[160:161]
	v_pk_mul_f32 v[154:155], v[154:155], v[166:167]
	v_pk_mul_f32 v[4:5], v[4:5], v[128:129]
	v_pk_mul_f32 v[6:7], v[6:7], v[130:131]
	v_pk_mul_f32 v[0:1], v[0:1], v[152:153]
	v_pk_mul_f32 v[2:3], v[2:3], v[154:155]
	s_branch .LBB0_322

; DEV bf16_t f2bf(float f) { return (bf16_t)(cvt_pk_bf16(f, 0.f) & 0xffffu); }
; DEV float bf2f(unsigned h) { return __uint_as_float(h << 16); }
; DEV float sigmoidf_(float x) { return 1.0f / (1.0f + __expf(-x)); }
; DEV void ret_sample_item(const Params& p, int l, int item, unsigned char* smem) {
;     ...
;   {
;     const int i = w;
;     const float qd = __expf(lg * (float)(i + 1));
;     float o[2]; float ss = 0.f;
; #pragma unroll
;     for (int c = 0; c < 2; ++c) {
;       const int e = lane + c * 64;
;       float a = qd * (part[(0 * 8 + i) * 128 + e] + part[(1 * 8 + i) * 128 + e] + part[(2 * 8 + i) * 128 + e] + part[(3 * 8 + i) * 128 + e]);
;       for (int j = 0; j <= i; ++j) a += inn[i * 8 + j] * vs[j * 128 + e];
;       o[c] = a; ss += a * a;
;     }
;     ss = wave_sum(ss);
;     const float rstd = rsqrtf(ss * (1.0f / 128.0f) + 1e-6f);
; #pragma unroll
;     for (int c = 0; c < 2; ++c) {
;       bf16_t* zp = Z + (rowbase + i) * NIN + RG + h * 128 + lane + c * 64;
;       const float g = bf2f(*zp);
;       *zp = f2bf(g * sigmoidf_(g) * o[c] * rstd);
;     }
.LBB0_335:
	s_or_b64 exec, exec, s[0:1]
	v_pk_mul_f32 v[2:3], v[0:1], v[0:1]
	v_xor_b32_e32 v4, 32, v202
	v_add_f32_e32 v2, v2, v3
	v_and_b32_e32 v3, 64, v202
	v_add_u32_e32 v3, 64, v3
	v_cmp_lt_i32_e32 vcc, v4, v3
	s_mov_b32 s0, 0x800000
	s_lshl_b32 s6, s6, 1
	v_lshl_add_u64 v[106:107], v[64:65], 0, s[6:7]
	v_lshl_add_u64 v[106:107], v[106:107], 0, v[168:169]
	global_load_ushort v108, v[106:107], off offset:2048
	global_load_ushort v109, v[106:107], off offset:2176
	v_cndmask_b32_e32 v4, v202, v4, vcc
	v_lshlrev_b32_e32 v4, 2, v4
	ds_bpermute_b32 v4, v4, v2
	s_waitcnt lgkmcnt(0)
	v_add_f32_e32 v2, v2, v4
	v_xor_b32_e32 v4, 16, v202
	v_cmp_lt_i32_e32 vcc, v4, v3
	s_nop 1
	v_cndmask_b32_e32 v4, v202, v4, vcc
	v_lshlrev_b32_e32 v4, 2, v4
	ds_bpermute_b32 v4, v4, v2
	s_waitcnt lgkmcnt(0)
	v_add_f32_e32 v2, v2, v4
	v_xor_b32_e32 v4, 8, v202
	v_cmp_lt_i32_e32 vcc, v4, v3
	s_nop 1
	v_cndmask_b32_e32 v4, v202, v4, vcc
	v_lshlrev_b32_e32 v4, 2, v4
	ds_bpermute_b32 v4, v4, v2
	s_waitcnt lgkmcnt(0)
	v_add_f32_e32 v2, v2, v4
	v_xor_b32_e32 v4, 4, v202
	v_cmp_lt_i32_e32 vcc, v4, v3
	s_nop 1
	v_cndmask_b32_e32 v4, v202, v4, vcc
	v_lshlrev_b32_e32 v4, 2, v4
	ds_bpermute_b32 v4, v4, v2
	s_waitcnt lgkmcnt(0)
	v_add_f32_e32 v2, v2, v4
	v_xor_b32_e32 v4, 2, v202
	v_cmp_lt_i32_e32 vcc, v4, v3
	s_nop 1
	v_cndmask_b32_e32 v4, v202, v4, vcc
	v_lshlrev_b32_e32 v4, 2, v4
	ds_bpermute_b32 v4, v4, v2
	s_waitcnt lgkmcnt(0)
	v_add_f32_e32 v2, v2, v4
	v_xor_b32_e32 v4, 1, v202
	v_cmp_lt_i32_e32 vcc, v4, v3
	s_nop 1
	v_cndmask_b32_e32 v3, v202, v4, vcc
	v_lshlrev_b32_e32 v3, 2, v3
	ds_bpermute_b32 v3, v3, v2
	s_waitcnt lgkmcnt(0)
	v_add_f32_e32 v2, v2, v3
	v_fmamk_f32 v2, v2, 0x3c000000, v170
	v_cmp_gt_f32_e32 vcc, s0, v2
	v_mul_f32_e32 v3, 0x4b800000, v2
	s_nop 0
	v_cndmask_b32_e32 v2, v2, v3, vcc
	v_rsq_f32_e32 v2, v2
	s_nop 0
	v_mul_f32_e32 v3, 0x45800000, v2
	v_cndmask_b32_e32 v4, v2, v3, vcc
	s_waitcnt vmcnt(1)
	v_lshlrev_b32_e32 v5, 16, v108
	v_mul_f32_e32 v6, 0xbfb8aa3b, v5
	v_exp_f32_e32 v6, v6
	s_nop 0
	v_add_f32_e32 v6, 1.0, v6
	v_rcp_f32_e32 v8, v6
	s_nop 0
	v_fma_f32 v9, -v6, v8, 1.0
	v_fmac_f32_e32 v8, v9, v8
	v_mov_b32_e32 v6, v8
	v_mul_f32_e32 v5, v6, v5
	v_mul_f32_e32 v0, v0, v5
	v_mul_f32_e32 v0, v4, v0
	v_cvt_pk_bf16_f32 v0, v0, s0
	global_store_short v[106:107], v0, off offset:2048
	s_waitcnt vmcnt(1)
	v_lshlrev_b32_e32 v0, 16, v109
	v_mul_f32_e32 v5, 0xbfb8aa3b, v0
	v_exp_f32_e32 v5, v5
	s_nop 0
	v_add_f32_e32 v5, 1.0, v5
	v_rcp_f32_e32 v7, v5
	s_nop 0
	v_fma_f32 v8, -v5, v7, 1.0
	v_fmac_f32_e32 v7, v8, v7
	v_mov_b32_e32 v5, v7
	v_mul_f32_e32 v0, v5, v0
	v_mul_f32_e32 v0, v1, v0
	v_mul_f32_e32 v0, v4, v0
	v_cvt_pk_bf16_f32 v0, v0, s0
	global_store_short v[106:107], v0, off offset:2176
	s_barrier

; DEV f32x4 mfma32(bf16x8 a, bf16x8 b, f32x4 c) { return __builtin_amdgcn_mfma_f32_16x16x32_bf16(a, b, c, 0, 0, 0); }
; DEV void attn_sample_item(const Params& p, int l, int item, unsigned char* smem) {
;     ...
;     if (tid < 256) *(u32x4*)(Qs + (tid >> 3) * 144 + (tid & 7) * 16) = qv;
;   }
;   __syncthreads();
;   {
;     const int qt = w & 1, dt = w >> 1;
;     const int r = qt * 16 + fr, qi = r & 7, hh = kvh * 4 + (r >> 3);
;     bf16x8 qf[2];
; #pragma unroll
;     for (int ks = 0; ks < 2; ++ks) qf[ks] = *(const bf16x8*)(Qs + r * 144 + ks * 64 + fq * 16);
;     f32x4 s[9];
; #pragma unroll
;     for (int t = 0; t < 9; ++t) {
;       s[t] = (f32x4){0.f, 0.f, 0.f, 0.f};
; #pragma unroll
;       for (int ks = 0; ks < 2; ++ks) {
;         const bf16x8 kf = *(const bf16x8*)(Ks + (t * 16 + fr) * 144 + ks * 64 + fq * 16);
;         s[t] = mfma32(kf, qf[ks], s[t]);
;       }
;     }
;     const float slope = exp2f(-(float)(hh + 1));
;     const float sink = p.in[I_SINKS][l * 8 + hh];
;     float mx = sink;
; #pragma unroll
;     for (int t = 0; t < 9; ++t)
; #pragma unroll
;       for (int j = 0; j < 4; ++j) {
;         const int kj = t * 16 + fq * 4 + j;
;         const bool okk = (kj > qi) && (kj <= 128 + qi);
;         const float sc = okk ? s[t][j] * 0.125f - slope * (float)(128 + qi - kj) : -INFINITY;
;         s[t][j] = sc; mx = fmaxf(mx, sc);
;       }
.LBB0_350:
	s_or_b64 exec, exec, s[2:3]
	s_and_saveexec_b64 s[0:1], vcc
	v_add3_u32 v4, 0, v4, v38
	ds_write_b128 v4, v[0:3] offset:40192
	s_or_b64 exec, exec, s[0:1]
	v_lshlrev_b32_e32 v0, 4, v36
	v_and_b32_e32 v38, 15, v47
	v_and_b32_e32 v39, 16, v0
	v_and_b32_e32 v1, 48, v47
	v_or_b32_e32 v0, v39, v38
	v_add_u32_e32 v1, 0, v1
	v_lshrrev_b32_e32 v36, 3, v0
	v_mad_u32_u24 v0, v0, s33, v1
	v_mad_u32_u24 v37, v38, s33, v1
	s_waitcnt lgkmcnt(0)
	s_barrier
	ds_read_b128 v[32:35], v0 offset:40192
	ds_read_b128 v[50:53], v0 offset:40256
	ds_read_b128 v[0:3], v37
	ds_read_b128 v[4:7], v37 offset:64
	s_waitcnt lgkmcnt(1)
	v_mfma_f32_16x16x32_bf16 v[0:3], v[0:3], v[32:35], 0
	s_lshl_b32 s2, s26, 2
	v_or_b32_e32 v36, s2, v36
	v_or_b32_e32 v44, s18, v36
	s_waitcnt lgkmcnt(0)
	v_mfma_f32_16x16x32_bf16 v[28:31], v[4:7], v[50:53], v[0:3]
	ds_read_b128 v[4:7], v37 offset:2368
	v_ashrrev_i32_e32 v45, 31, v44
	v_lshl_add_u64 v[44:45], v[44:45], 2, s[82:83]
	ds_read_b128 v[0:3], v37 offset:2304
	s_waitcnt lgkmcnt(0)
	v_mfma_f32_16x16x32_bf16 v[0:3], v[0:3], v[32:35], 0
	global_load_dword v42, v[44:45], off
	v_lshrrev_b32_e32 v40, 4, v49
	v_and_b32_e32 v43, 7, v47
	v_mfma_f32_16x16x32_bf16 v[24:27], v[4:7], v[50:53], v[0:3]
	ds_read_b128 v[4:7], v37 offset:4672
	v_lshlrev_b32_e32 v168, 1, v38
	ds_read_b128 v[54:57], v37 offset:16192
	s_nop 0
	ds_read_b128 v[0:3], v37 offset:4608
	s_waitcnt lgkmcnt(0)
	v_mfma_f32_16x16x32_bf16 v[0:3], v[0:3], v[32:35], 0
	v_mfma_f32_16x16x32_bf16 v[20:23], v[4:7], v[50:53], v[0:3]
	ds_read_b128 v[4:7], v37 offset:6976
	s_nop 5
	ds_read_b128 v[0:3], v37 offset:6912
	s_waitcnt lgkmcnt(0)
	v_mfma_f32_16x16x32_bf16 v[0:3], v[0:3], v[32:35], 0
	v_mfma_f32_16x16x32_bf16 v[16:19], v[4:7], v[50:53], v[0:3]
	ds_read_b128 v[4:7], v37 offset:9280
	s_nop 5
	ds_read_b128 v[0:3], v37 offset:9216
	s_waitcnt lgkmcnt(0)
	v_mfma_f32_16x16x32_bf16 v[0:3], v[0:3], v[32:35], 0
	v_mfma_f32_16x16x32_bf16 v[12:15], v[4:7], v[50:53], v[0:3]
	ds_read_b128 v[4:7], v37 offset:11584
	s_nop 5
	ds_read_b128 v[0:3], v37 offset:11520
	s_waitcnt lgkmcnt(0)
	v_mfma_f32_16x16x32_bf16 v[0:3], v[0:3], v[32:35], 0
	v_mfma_f32_16x16x32_bf16 v[8:11], v[4:7], v[50:53], v[0:3]
	ds_read_b128 v[4:7], v37 offset:13888
	s_nop 5
	ds_read_b128 v[0:3], v37 offset:13824
	s_waitcnt lgkmcnt(0)
	v_mfma_f32_16x16x32_bf16 v[0:3], v[0:3], v[32:35], 0
	v_mfma_f32_16x16x32_bf16 v[4:7], v[4:7], v[50:53], v[0:3]
	s_nop 6
	ds_read_b128 v[0:3], v37 offset:16128
	s_waitcnt lgkmcnt(0)
	v_mfma_f32_16x16x32_bf16 v[0:3], v[0:3], v[32:35], 0
	v_mfma_f32_16x16x32_bf16 v[0:3], v[54:57], v[50:53], v[0:3]
	ds_read_b128 v[54:57], v37 offset:18432
	s_waitcnt lgkmcnt(0)
	v_mfma_f32_16x16x32_bf16 v[32:35], v[54:57], v[32:35], 0
	ds_read_b128 v[54:57], v37 offset:18496
	v_add_u32_e32 v37, 1, v36
	v_cvt_f32_ubyte0_e32 v37, v37
	v_cmp_lt_f32_e32 vcc, s41, v37
	s_waitcnt lgkmcnt(0)
	v_mfma_f32_16x16x32_bf16 v[32:35], v[54:57], v[50:53], v[32:35]
	v_cndmask_b32_e32 v41, 0, v203, vcc
	v_sub_f32_e32 v37, v41, v37
	v_exp_f32_e32 v37, v37
	v_cndmask_b32_e32 v41, 0, v207, vcc
	v_or_b32_e32 v51, 0x80, v43
	v_ldexp_f32 v37, v37, v41
	v_lshlrev_b32_e32 v41, 2, v40
	v_sub_u32_e32 v36, v51, v41
	v_cvt_f32_ubyte0_e32 v179, v36
	v_mov_b32_e32 v36, v28
	v_pk_mul_f32 v[44:45], v[36:37], v[178:179]
	v_sub_co_u32_e32 v52, vcc, v43, v41
	v_sub_f32_e32 v28, v44, v45
	s_nop 0
	v_cndmask_b32_e32 v44, v205, v28, vcc
	v_xad_u32 v28, v41, -1, v51
	v_cvt_f32_ubyte0_e32 v179, v28
	v_mov_b32_e32 v36, v29
	v_pk_mul_f32 v[28:29], v[36:37], v[178:179]
	v_cmp_le_u32_e64 s[0:1], v43, v41
	v_sub_f32_e32 v28, v28, v29
	v_mov_b32_e32 v36, v30
	v_cndmask_b32_e64 v45, v205, v28, s[0:1]
	v_or_b32_e32 v28, 2, v41
	v_cmp_gt_u32_e64 s[0:1], v28, v43
	v_sub_u32_e32 v28, v51, v28
	v_cvt_f32_ubyte0_e32 v179, v28
	v_pk_mul_f32 v[28:29], v[36:37], v[178:179]
	v_mov_b32_e32 v36, v31
	v_sub_f32_e32 v28, v28, v29
	v_cndmask_b32_e64 v46, v205, v28, s[0:1]
	v_or_b32_e32 v28, 3, v41
	v_cmp_gt_u32_e64 s[0:1], v28, v43
	v_sub_u32_e32 v28, v51, v28
	v_cvt_f32_ubyte0_e32 v179, v28
	v_pk_mul_f32 v[28:29], v[36:37], v[178:179]
	v_sub_u32_e32 v50, v43, v41
	v_sub_f32_e32 v28, v28, v29
	v_cndmask_b32_e64 v49, v205, v28, s[0:1]
	v_add_u32_e32 v28, 14, v50
	v_cvt_f32_u32_e32 v179, v28
	v_mov_b32_e32 v36, v2
	s_movk_i32 s0, 0x130
	v_pk_mul_f32 v[28:29], v[36:37], v[178:179]
	s_nop 0
	v_sub_f32_e32 v2, v28, v29
	v_add_u32_e32 v28, 13, v50
	v_cvt_f32_u32_e32 v179, v28
	v_mov_b32_e32 v36, v3
	v_pk_mul_f32 v[28:29], v[36:37], v[178:179]
	v_cvt_f32_u32_e32 v179, v52
	v_mov_b32_e32 v36, v32
	v_sub_f32_e32 v3, v28, v29
	v_pk_mul_f32 v[28:29], v[36:37], v[178:179]
	s_nop 0
	v_sub_f32_e32 v28, v28, v29
	v_or_b32_e32 v29, 0x81, v41
	v_cndmask_b32_e32 v28, v28, v205, vcc
	v_sub_co_u32_e32 v29, vcc, v51, v29
	v_cvt_f32_u32_e32 v179, v29
	v_mov_b32_e32 v36, v33
	v_pk_mul_f32 v[30:31], v[36:37], v[178:179]
	s_nop 0
	v_sub_f32_e32 v29, v30, v31
	v_or_b32_e32 v30, 0x82, v41
	v_cndmask_b32_e32 v29, v29, v205, vcc
	v_sub_co_u32_e32 v30, vcc, v51, v30
	v_cvt_f32_u32_e32 v179, v30
	v_mov_b32_e32 v36, v34
	v_pk_mul_f32 v[30:31], v[36:37], v[178:179]
	s_nop 0
	v_sub_f32_e32 v30, v30, v31
	v_or_b32_e32 v31, 0x83, v41
	v_cndmask_b32_e32 v30, v30, v205, vcc
	v_sub_co_u32_e32 v31, vcc, v51, v31
	v_cvt_f32_u32_e32 v179, v31
	v_mov_b32_e32 v36, v35
	v_pk_mul_f32 v[32:33], v[36:37], v[178:179]
	s_nop 0
	v_sub_f32_e32 v31, v32, v33
	s_waitcnt vmcnt(0)
; DEV void attn_sample_item(const Params& p, int l, int item, unsigned char* smem) {
;     ...
;     for (int t = 0; t < 9; ++t)
; #pragma unroll
;       for (int j = 0; j < 4; ++j) {
;         const int kj = t * 16 + fq * 4 + j;
;         const bool okk = (kj > qi) && (kj <= 128 + qi);
;         const float sc = okk ? s[t][j] * 0.125f - slope * (float)(128 + qi - kj) : -INFINITY;
;         s[t][j] = sc; mx = fmaxf(mx, sc);
;       }
;     mx = fmaxf(mx, __shfl_xor(mx, 16)); mx = fmaxf(mx, __shfl_xor(mx, 32));
	v_max3_f32 v32, v42, v44, v45
	v_max3_f32 v34, v32, v46, v49
	v_or_b32_e32 v32, 0x70, v43
	v_sub_u32_e32 v32, v32, v41
	v_cvt_f32_ubyte0_e32 v179, v32
	v_mov_b32_e32 v36, v24
	v_pk_mul_f32 v[32:33], v[36:37], v[178:179]
	v_mov_b32_e32 v36, v25
	v_sub_f32_e32 v24, v32, v33
	v_add_u32_e32 v32, 0x6f, v50
	v_cvt_f32_u32_e32 v179, v32
	v_cndmask_b32_e32 v31, v31, v205, vcc
	v_pk_mul_f32 v[32:33], v[36:37], v[178:179]
	s_nop 0
	v_sub_f32_e32 v25, v32, v33
	v_add_u32_e32 v32, 0x6e, v50
	v_cvt_f32_u32_e32 v179, v32
	v_mov_b32_e32 v36, v26
	v_max3_f32 v34, v34, v24, v25
	v_pk_mul_f32 v[32:33], v[36:37], v[178:179]
	s_nop 0
	v_sub_f32_e32 v26, v32, v33
	v_add_u32_e32 v32, 0x6d, v50
	v_cvt_f32_u32_e32 v179, v32
	v_mov_b32_e32 v36, v27
	v_pk_mul_f32 v[32:33], v[36:37], v[178:179]
	s_nop 0
	v_sub_f32_e32 v27, v32, v33
	v_or_b32_e32 v32, 0x60, v43
	v_sub_u32_e32 v32, v32, v41
	v_cvt_f32_ubyte0_e32 v179, v32
	v_mov_b32_e32 v36, v20
	v_pk_mul_f32 v[32:33], v[36:37], v[178:179]
	v_mov_b32_e32 v36, v21
	v_sub_f32_e32 v20, v32, v33
	v_add_u32_e32 v32, 0x5f, v50
	v_cvt_f32_u32_e32 v179, v32
	v_max3_f32 v34, v34, v26, v27
	v_pk_mul_f32 v[32:33], v[36:37], v[178:179]
	s_nop 0
	v_sub_f32_e32 v21, v32, v33
	v_add_u32_e32 v32, 0x5e, v50
	v_cvt_f32_u32_e32 v179, v32
	v_mov_b32_e32 v36, v22
	v_add_u32_e32 v22, 0x5d, v50
	v_max3_f32 v34, v34, v20, v21
	v_pk_mul_f32 v[32:33], v[36:37], v[178:179]
	v_cvt_f32_u32_e32 v179, v22
	v_mov_b32_e32 v36, v23
	v_sub_f32_e32 v32, v32, v33
	v_pk_mul_f32 v[22:23], v[36:37], v[178:179]
	s_nop 0
	v_sub_f32_e32 v33, v22, v23
	v_or_b32_e32 v22, 0x50, v43
	v_sub_u32_e32 v22, v22, v41
	v_cvt_f32_ubyte0_e32 v179, v22
	v_mov_b32_e32 v36, v16
	v_add_u32_e32 v16, 0x4f, v50
	v_pk_mul_f32 v[22:23], v[36:37], v[178:179]
	v_cvt_f32_u32_e32 v179, v16
	v_mov_b32_e32 v36, v17
	v_sub_f32_e32 v22, v22, v23
	v_max3_f32 v34, v34, v32, v33
	v_pk_mul_f32 v[16:17], v[36:37], v[178:179]
	v_mov_b32_e32 v36, v18
	v_sub_f32_e32 v23, v16, v17
	v_add_u32_e32 v16, 0x4e, v50
	v_cvt_f32_u32_e32 v179, v16
	v_max3_f32 v34, v34, v22, v23
	v_pk_mul_f32 v[16:17], v[36:37], v[178:179]
	s_nop 0
	v_sub_f32_e32 v18, v16, v17
	v_add_u32_e32 v16, 0x4d, v50
	v_cvt_f32_u32_e32 v179, v16
	v_mov_b32_e32 v36, v19
	v_pk_mul_f32 v[16:17], v[36:37], v[178:179]
	s_nop 0
	v_sub_f32_e32 v19, v16, v17
	v_or_b32_e32 v16, 64, v43
	v_sub_u32_e32 v16, v16, v41
	v_cvt_f32_ubyte0_e32 v179, v16
	v_mov_b32_e32 v36, v12
	v_add_u32_e32 v12, 63, v50
	v_pk_mul_f32 v[16:17], v[36:37], v[178:179]
	v_cvt_f32_u32_e32 v179, v12
	v_mov_b32_e32 v36, v13
	v_sub_f32_e32 v16, v16, v17
	v_max3_f32 v34, v34, v18, v19
	v_pk_mul_f32 v[12:13], v[36:37], v[178:179]
	v_mov_b32_e32 v36, v14
	v_sub_f32_e32 v17, v12, v13
	v_add_u32_e32 v12, 62, v50
	v_cvt_f32_u32_e32 v179, v12
	v_max3_f32 v34, v34, v16, v17
	v_pk_mul_f32 v[12:13], v[36:37], v[178:179]
	s_nop 0
	v_sub_f32_e32 v14, v12, v13
	v_add_u32_e32 v12, 61, v50
	v_cvt_f32_u32_e32 v179, v12
	v_mov_b32_e32 v36, v15
	v_pk_mul_f32 v[12:13], v[36:37], v[178:179]
	s_nop 0
	v_sub_f32_e32 v15, v12, v13
	v_or_b32_e32 v12, 48, v43
	v_sub_u32_e32 v12, v12, v41
	v_cvt_f32_ubyte0_e32 v179, v12
	v_mov_b32_e32 v36, v8
	v_add_u32_e32 v8, 47, v50
	v_pk_mul_f32 v[12:13], v[36:37], v[178:179]
	v_cvt_f32_u32_e32 v179, v8
	v_mov_b32_e32 v36, v9
	v_sub_f32_e32 v12, v12, v13
	v_max3_f32 v34, v34, v14, v15
	v_pk_mul_f32 v[8:9], v[36:37], v[178:179]
	v_mov_b32_e32 v36, v10
	v_sub_f32_e32 v13, v8, v9
	v_add_u32_e32 v8, 46, v50
	v_cvt_f32_u32_e32 v179, v8
	v_max3_f32 v34, v34, v12, v13
	v_pk_mul_f32 v[8:9], v[36:37], v[178:179]
	s_nop 0
	v_sub_f32_e32 v10, v8, v9
	v_add_u32_e32 v8, 45, v50
	v_cvt_f32_u32_e32 v179, v8
	v_mov_b32_e32 v36, v11
	v_pk_mul_f32 v[8:9], v[36:37], v[178:179]
	s_nop 0
	v_sub_f32_e32 v11, v8, v9
	v_or_b32_e32 v8, 32, v43
	v_sub_u32_e32 v8, v8, v41
	v_cvt_f32_ubyte0_e32 v179, v8
	v_mov_b32_e32 v36, v4
	v_add_u32_e32 v4, 31, v50
	v_pk_mul_f32 v[8:9], v[36:37], v[178:179]
	v_cvt_f32_u32_e32 v179, v4
	v_mov_b32_e32 v36, v5
	v_sub_f32_e32 v8, v8, v9
	v_max3_f32 v34, v34, v10, v11
	v_pk_mul_f32 v[4:5], v[36:37], v[178:179]
	v_mov_b32_e32 v36, v6
	v_sub_f32_e32 v9, v4, v5
	v_add_u32_e32 v4, 30, v50
	v_cvt_f32_u32_e32 v179, v4
	v_max3_f32 v34, v34, v8, v9
	v_pk_mul_f32 v[4:5], v[36:37], v[178:179]
	s_nop 0
	v_sub_f32_e32 v6, v4, v5
	v_add_u32_e32 v4, 29, v50
	v_cvt_f32_u32_e32 v179, v4
	v_mov_b32_e32 v36, v7
	v_pk_mul_f32 v[4:5], v[36:37], v[178:179]
	s_nop 0
	v_sub_f32_e32 v7, v4, v5
	v_or_b32_e32 v4, 16, v43
	v_sub_u32_e32 v4, v4, v41
	v_cvt_f32_ubyte0_e32 v179, v4
	v_mov_b32_e32 v36, v0
	v_add_u32_e32 v0, 15, v50
	v_pk_mul_f32 v[4:5], v[36:37], v[178:179]
	v_cvt_f32_u32_e32 v179, v0
	v_mov_b32_e32 v36, v1
	v_max3_f32 v34, v34, v6, v7
	v_sub_f32_e32 v5, v4, v5
	v_pk_mul_f32 v[0:1], v[36:37], v[178:179]
	v_and_b32_e32 v4, 64, v202
	v_sub_f32_e32 v0, v0, v1
	v_max3_f32 v1, v34, v5, v0
	v_xor_b32_e32 v34, 16, v202
	v_add_u32_e32 v35, 64, v4
	v_max3_f32 v1, v1, v2, v3
	v_cmp_lt_i32_e32 vcc, v34, v35
	v_max3_f32 v1, v1, v28, v29
	v_max3_f32 v1, v1, v30, v31
	v_cndmask_b32_e32 v34, v202, v34, vcc
	v_lshlrev_b32_e32 v34, 2, v34
	ds_bpermute_b32 v36, v34, v1
	v_or_b32_e32 v4, v4, v41
	s_waitcnt lgkmcnt(0)
	v_max_f32_e32 v36, v36, v36
	v_max_f32_e32 v1, v1, v36
	v_xor_b32_e32 v36, 32, v202
	v_cmp_lt_i32_e32 vcc, v36, v35
	s_nop 1
	v_cndmask_b32_e32 v35, v202, v36, vcc
	v_lshlrev_b32_e32 v35, 2, v35
	ds_bpermute_b32 v36, v35, v1
	s_waitcnt lgkmcnt(0)
; DEV void attn_sample_item(const Params& p, int l, int item, unsigned char* smem) {
;     ...
;     float sum = 0.f;
; #pragma unroll
;     for (int t = 0; t < 9; ++t)
; #pragma unroll
;       for (int j = 0; j < 4; ++j) { const float e = __expf(s[t][j] - mx); s[t][j] = e; sum += e; }
;     sum += __shfl_xor(sum, 16); sum += __shfl_xor(sum, 32);
;     const float denom = sum + __expf(sink - mx);
;     f32x4 o = (f32x4){0.f, 0.f, 0.f, 0.f};
; #pragma unroll
;     for (int t = 0; t < 9; ++t) {
;       const bf16x4 pf = pack4(s[t][0], s[t][1], s[t][2], s[t][3]);
	v_max_f32_e32 v36, v36, v36
	v_max_f32_e32 v1, v1, v36
	v_sub_f32_e32 v36, v44, v1
	v_mul_f32_e32 v36, 0x3fb8aa3b, v36
	v_sub_f32_e32 v43, v45, v1
	v_exp_f32_e32 v36, v36
	v_mul_f32_e32 v43, 0x3fb8aa3b, v43
	v_sub_f32_e32 v44, v46, v1
	v_exp_f32_e32 v43, v43
	v_mul_f32_e32 v44, 0x3fb8aa3b, v44
	v_sub_f32_e32 v45, v49, v1
	v_exp_f32_e32 v44, v44
	v_mul_f32_e32 v45, 0x3fb8aa3b, v45
	v_sub_f32_e32 v24, v24, v1
	v_exp_f32_e32 v45, v45
	v_mul_f32_e32 v24, 0x3fb8aa3b, v24
	v_sub_f32_e32 v25, v25, v1
	v_add_f32_e32 v37, 0, v36
	v_exp_f32_e32 v24, v24
	v_mul_f32_e32 v25, 0x3fb8aa3b, v25
	v_sub_f32_e32 v26, v26, v1
	v_add_f32_e32 v37, v43, v37
	v_exp_f32_e32 v25, v25
	v_mul_f32_e32 v26, 0x3fb8aa3b, v26
	v_sub_f32_e32 v27, v27, v1
	v_add_f32_e32 v37, v44, v37
	v_exp_f32_e32 v26, v26
	v_mul_f32_e32 v27, 0x3fb8aa3b, v27
	v_sub_f32_e32 v20, v20, v1
	v_add_f32_e32 v37, v45, v37
	v_exp_f32_e32 v27, v27
	v_mul_f32_e32 v20, 0x3fb8aa3b, v20
	v_sub_f32_e32 v21, v21, v1
	v_add_f32_e32 v37, v24, v37
	v_exp_f32_e32 v20, v20
	v_mul_f32_e32 v21, 0x3fb8aa3b, v21
	v_sub_f32_e32 v32, v32, v1
	v_add_f32_e32 v37, v25, v37
	v_exp_f32_e32 v21, v21
	v_mul_f32_e32 v32, 0x3fb8aa3b, v32
	v_sub_f32_e32 v33, v33, v1
	v_add_f32_e32 v37, v26, v37
	v_exp_f32_e32 v32, v32
	v_mul_f32_e32 v33, 0x3fb8aa3b, v33
	v_sub_f32_e32 v22, v22, v1
	v_add_f32_e32 v37, v27, v37
	v_exp_f32_e32 v33, v33
	v_mul_f32_e32 v22, 0x3fb8aa3b, v22
	v_sub_f32_e32 v23, v23, v1
	v_add_f32_e32 v37, v20, v37
	v_exp_f32_e32 v22, v22
	v_mul_f32_e32 v23, 0x3fb8aa3b, v23
	v_sub_f32_e32 v18, v18, v1
	v_add_f32_e32 v37, v21, v37
	v_exp_f32_e32 v23, v23
	v_mul_f32_e32 v18, 0x3fb8aa3b, v18
	v_sub_f32_e32 v19, v19, v1
	v_add_f32_e32 v37, v32, v37
	v_exp_f32_e32 v18, v18
	v_mul_f32_e32 v19, 0x3fb8aa3b, v19
	v_sub_f32_e32 v16, v16, v1
	v_add_f32_e32 v37, v33, v37
	v_exp_f32_e32 v19, v19
	v_mul_f32_e32 v16, 0x3fb8aa3b, v16
	v_sub_f32_e32 v17, v17, v1
	v_add_f32_e32 v37, v22, v37
	v_exp_f32_e32 v16, v16
	v_mul_f32_e32 v17, 0x3fb8aa3b, v17
	v_sub_f32_e32 v14, v14, v1
	v_add_f32_e32 v37, v23, v37
	v_exp_f32_e32 v17, v17
	v_mul_f32_e32 v14, 0x3fb8aa3b, v14
	v_sub_f32_e32 v15, v15, v1
	v_add_f32_e32 v37, v18, v37
	v_exp_f32_e32 v14, v14
	v_mul_f32_e32 v15, 0x3fb8aa3b, v15
	v_sub_f32_e32 v12, v12, v1
	v_add_f32_e32 v37, v19, v37
	v_exp_f32_e32 v15, v15
	v_mul_f32_e32 v12, 0x3fb8aa3b, v12
	v_add_f32_e32 v37, v16, v37
	v_exp_f32_e32 v46, v12
	v_add_f32_e32 v37, v17, v37
	v_add_f32_e32 v37, v14, v37
	v_sub_f32_e32 v13, v13, v1
	v_add_f32_e32 v37, v15, v37
	v_mul_f32_e32 v13, 0x3fb8aa3b, v13
	v_sub_f32_e32 v10, v10, v1
	v_add_f32_e32 v12, v46, v37
	v_exp_f32_e32 v37, v13
	v_mul_f32_e32 v10, 0x3fb8aa3b, v10
	v_sub_f32_e32 v11, v11, v1
	v_exp_f32_e32 v49, v10
	v_mul_f32_e32 v11, 0x3fb8aa3b, v11
	v_sub_f32_e32 v8, v8, v1
	v_exp_f32_e32 v11, v11
	v_mul_f32_e32 v8, 0x3fb8aa3b, v8
	v_sub_f32_e32 v9, v9, v1
	v_sub_f32_e32 v2, v2, v1
	v_exp_f32_e32 v50, v8
	v_mul_f32_e32 v9, 0x3fb8aa3b, v9
	v_sub_f32_e32 v6, v6, v1
	v_mul_f32_e32 v2, 0x3fb8aa3b, v2
	v_add_f32_e32 v12, v37, v12
	v_exp_f32_e32 v51, v9
	v_mul_f32_e32 v6, 0x3fb8aa3b, v6
	v_sub_f32_e32 v7, v7, v1
	v_exp_f32_e32 v55, v2
	v_sub_f32_e32 v2, v3, v1
	v_add_f32_e32 v10, v49, v12
	v_exp_f32_e32 v52, v6
	v_mul_f32_e32 v7, 0x3fb8aa3b, v7
	v_sub_f32_e32 v5, v5, v1
	v_mul_f32_e32 v2, 0x3fb8aa3b, v2
	v_add_f32_e32 v10, v11, v10
	v_exp_f32_e32 v53, v7
	v_mul_f32_e32 v5, 0x3fb8aa3b, v5
	v_sub_f32_e32 v0, v0, v1
	v_exp_f32_e32 v56, v2
	v_sub_f32_e32 v2, v28, v1
	v_add_f32_e32 v8, v50, v10
	v_exp_f32_e32 v5, v5
	v_mul_f32_e32 v0, 0x3fb8aa3b, v0
	v_mul_f32_e32 v2, 0x3fb8aa3b, v2
	v_add_f32_e32 v8, v51, v8
	v_exp_f32_e32 v54, v0
	v_exp_f32_e32 v28, v2
	v_sub_f32_e32 v2, v29, v1
	v_add_f32_e32 v6, v52, v8
	v_mul_f32_e32 v2, 0x3fb8aa3b, v2
	v_add_f32_e32 v6, v53, v6
	v_exp_f32_e32 v29, v2
	v_sub_f32_e32 v2, v30, v1
	v_add_f32_e32 v6, v5, v6
	v_mul_f32_e32 v2, 0x3fb8aa3b, v2
	v_add_f32_e32 v0, v54, v6
	v_exp_f32_e32 v30, v2
	v_sub_f32_e32 v2, v31, v1
	v_add_f32_e32 v0, v55, v0
	v_mul_f32_e32 v2, 0x3fb8aa3b, v2
	v_add_f32_e32 v0, v56, v0
	v_exp_f32_e32 v31, v2
	v_add_f32_e32 v0, v28, v0
	v_add_f32_e32 v0, v29, v0
	v_add_f32_e32 v0, v30, v0
	v_add_f32_e32 v0, v31, v0
	ds_bpermute_b32 v2, v34, v0
	v_cvt_pk_bf16_f32 v6, v36, v43
	v_cvt_pk_bf16_f32 v7, v44, v45
	v_cvt_pk_bf16_f32 v12, v20, v21
	v_cvt_pk_bf16_f32 v13, v32, v33
	s_waitcnt lgkmcnt(0)
; DEV bf16_t f2bf(float f) { return (bf16_t)(cvt_pk_bf16(f, 0.f) & 0xffffu); }
; DEV f32x4 mfma16(bf16x4 a, bf16x4 b, f32x4 c) { return __builtin_amdgcn_mfma_f32_16x16x16bf16_1k(a, b, c, 0, 0, 0); }
; DEV void attn_sample_item(const Params& p, int l, int item, unsigned char* smem) {
;     ...
;     sum += __shfl_xor(sum, 16); sum += __shfl_xor(sum, 32);
;     const float denom = sum + __expf(sink - mx);
;     f32x4 o = (f32x4){0.f, 0.f, 0.f, 0.f};
; #pragma unroll
;     for (int t = 0; t < 9; ++t) {
;       const bf16x4 pf = pack4(s[t][0], s[t][1], s[t][2], s[t][3]);
;       const bf16x4 vf = *(const bf16x4*)(Vt + (dt * 16 + fr) * 152 + t * 16 + fq * 4);
;       o = mfma16(pf, vf, o);
;     }
; #pragma unroll
;     for (int j = 0; j < 4; ++j) {
;       const int ro = qt * 16 + fq * 4 + j;
;       const float inv = 1.0f / __shfl(denom, fq * 4 + j);
;       Z[(rowbase + (ro & 7)) * NIN + AQ + (kvh * 4 + (ro >> 3)) * 64 + dt * 16 + fr] = f2bf(o[j] * inv);
;     }
	v_add_f32_e32 v34, v0, v2
	v_sub_f32_e32 v0, v42, v1
	v_mul_f32_e32 v0, 0x3fb8aa3b, v0
	v_exp_f32_e32 v42, v0
	v_bfi_b32 v0, -16, v48, v47
	v_mul_lo_u32 v0, v0, s0
	v_lshlrev_b32_e32 v1, 3, v40
	v_add3_u32 v40, 0, v0, v1
	v_add_u32_e32 v36, 0x5000, v40
	ds_read2_b64 v[0:3], v36 offset0:32 offset1:36
	s_waitcnt lgkmcnt(0)
	v_mfma_f32_16x16x16_bf16 v[6:9], v[6:7], v[0:1], 0
	v_cvt_pk_bf16_f32 v0, v24, v25
	v_cvt_pk_bf16_f32 v1, v26, v27
	ds_bpermute_b32 v35, v35, v34
	v_and_b32_e32 v10, -16, v48
	v_mfma_f32_16x16x16_bf16 v[0:3], v[0:1], v[2:3], v[6:9]
	s_nop 2
	ds_read2_b64 v[6:9], v36 offset0:40 offset1:44
	s_waitcnt lgkmcnt(0)
	v_mfma_f32_16x16x16_bf16 v[0:3], v[12:13], v[6:7], v[0:3]
	v_cvt_pk_bf16_f32 v6, v22, v23
	v_cvt_pk_bf16_f32 v7, v18, v19
	v_cvt_pk_bf16_f32 v12, v16, v17
	v_cvt_pk_bf16_f32 v13, v14, v15
	v_mfma_f32_16x16x16_bf16 v[0:3], v[6:7], v[8:9], v[0:3]
	ds_read2_b64 v[6:9], v36 offset0:48 offset1:52
	s_waitcnt lgkmcnt(0)
	v_mfma_f32_16x16x16_bf16 v[0:3], v[12:13], v[6:7], v[0:3]
	v_cvt_pk_bf16_f32 v6, v46, v37
	v_cvt_pk_bf16_f32 v7, v49, v11
	v_cvt_pk_bf16_f32 v12, v50, v51
	v_cvt_pk_bf16_f32 v13, v52, v53
	v_mfma_f32_16x16x16_bf16 v[0:3], v[6:7], v[8:9], v[0:3]
	ds_read2_b64 v[6:9], v36 offset0:56 offset1:60
	v_ashrrev_i32_e32 v11, 31, v10
	s_waitcnt lgkmcnt(0)
	v_mfma_f32_16x16x16_bf16 v[0:3], v[12:13], v[6:7], v[0:3]
	v_cvt_pk_bf16_f32 v6, v5, v54
	v_cvt_pk_bf16_f32 v7, v55, v56
	v_add_f32_e32 v5, v34, v35
	s_nop 0
	v_mfma_f32_16x16x16_bf16 v[0:3], v[6:7], v[8:9], v[0:3]
	v_cvt_pk_bf16_f32 v6, v28, v29
	v_cvt_pk_bf16_f32 v7, v30, v31
	ds_read_b64 v[8:9], v40 offset:20992
	s_waitcnt lgkmcnt(0)
	v_mfma_f32_16x16x16_bf16 v[0:3], v[6:7], v[8:9], v[0:3]
	v_add_f32_e32 v8, v42, v5
	v_lshlrev_b32_e32 v9, 2, v4
	ds_bpermute_b32 v4, v9, v8
	v_lshl_add_u64 v[6:7], v[10:11], 1, s[30:31]
	v_or_b32_e32 v5, v39, v41
	v_lshrrev_b32_e32 v5, 3, v5
	v_or_b32_e32 v5, s2, v5
	s_waitcnt lgkmcnt(0)
	v_rcp_f32_e32 v11, v4
	v_lshl_add_u64 v[6:7], v[6:7], 0, v[168:169]
	v_fma_f32 v12, -v4, v11, 1.0
	v_fmac_f32_e32 v11, v12, v11
	v_mov_b32_e32 v4, v11
	v_mul_f32_e32 v0, v0, v4
	v_cvt_pk_bf16_f32 v0, v0, s0
	v_and_or_b32 v4, v41, 4, s6
	s_movk_i32 s0, 0x1b00
	v_mul_lo_u32 v4, v4, s0
	v_lshl_add_u32 v168, v5, 6, v4
	v_lshl_add_u64 v[4:5], v[168:169], 1, v[6:7]
	global_store_short v[4:5], v0, off offset:3072
	ds_bpermute_b32 v0, v9, v8 offset:4
	s_waitcnt lgkmcnt(0)
	v_rcp_f32_e32 v7, v0
	s_nop 0
	v_fma_f32 v10, -v0, v7, 1.0
	v_fmac_f32_e32 v7, v10, v7
	v_mov_b32_e32 v0, v7
	v_mul_f32_e32 v0, v1, v0
	v_cvt_pk_bf16_f32 v6, v0, s0
	v_add_co_u32_e32 v0, vcc, 0x4000, v4
	s_nop 1
	v_addc_co_u32_e32 v1, vcc, 0, v5, vcc
	global_store_short v[0:1], v6, off offset:512
	ds_bpermute_b32 v0, v9, v8 offset:8
	s_waitcnt lgkmcnt(0)
	v_rcp_f32_e32 v6, v0
	s_nop 0
	v_fma_f32 v7, -v0, v6, 1.0
	v_fmac_f32_e32 v6, v7, v6
	v_mov_b32_e32 v0, v6
	v_mul_f32_e32 v0, v2, v0
	v_cvt_pk_bf16_f32 v2, v0, s0
	v_add_co_u32_e32 v0, vcc, 0x7000, v4
	s_nop 1
	v_addc_co_u32_e32 v1, vcc, 0, v5, vcc
	global_store_short v[0:1], v2, off offset:2048
	ds_bpermute_b32 v0, v9, v8 offset:12
	s_waitcnt lgkmcnt(0)
	v_rcp_f32_e32 v2, v0
	s_nop 0
	v_fma_f32 v6, -v0, v2, 1.0
	v_fmac_f32_e32 v2, v6, v2
	v_mov_b32_e32 v0, v2
	v_mul_f32_e32 v0, v3, v0
	v_cvt_pk_bf16_f32 v2, v0, s0
	v_add_co_u32_e32 v0, vcc, 0xa000, v4
	s_mov_b64 s[0:1], 0
	s_nop 0
	v_addc_co_u32_e32 v1, vcc, 0, v5, vcc
	global_store_short v[0:1], v2, off offset:3584
	s_barrier
